# scan step loop 2 rows x 8 k per lane all packed f32; F1 A-tile rows staged permuted (4 consecutive tokens per lane) so fused conv epilogue needs DPP only for lane-crossing taps
# speedup vs baseline: 1.1415x; 1.0102x over previous
; __device__ __forceinline__ void scan_phase(const Params& p, int j, unsigned char* smem) {
;     ...
;             for (int t = 0; t < 16; ++t) {
;                 const float* op = OPS + t * 320 + kq * 16;
;                 f32x4 A4[4], B4[4], W4[4], K4[4], R4[4];
; #pragma unroll
;                 for (int i = 0; i < 4; ++i) A4[i] = *(const f32x4*)(op + i * 4);
; #pragma unroll
;                 for (int i = 0; i < 4; ++i) { W4[i] = *(const f32x4*)(op + 128 + i * 4); B4[i] = *(const f32x4*)(op + 64 + i * 4); K4[i] = *(const f32x4*)(op + 192 + i * 4); }
; #pragma unroll
;                 for (int i = 0; i < 4; ++i) R4[i] = *(const f32x4*)(op + 256 + i * 4);
;                 const float vv = VB[t * 64 + vrow];
.LBB0_509:
	v_lshlrev_b32_e32 v66, 2, v226
	v_and_b32_e32 v66, 32, v66
	v_add3_u32 v64, v23, v59, v66
	v_and_b32_e32 v66, 8, v226
	v_sub_u32_e32 v65, v62, v66
	v_lshl_add_u32 v65, s10, 2, v65
	s_movk_i32 s7, 0xf000
	s_waitcnt lgkmcnt(0)
	s_barrier
	v_add_u32_e32 v66, s7, v65
	ds_read_b128 v[68:71], v64
	ds_read_b128 v[72:75], v64 offset:16
	ds_read_b128 v[76:79], v64 offset:256
	ds_read_b128 v[80:83], v64 offset:272
	ds_read_b128 v[84:87], v64 offset:512
	ds_read_b128 v[88:91], v64 offset:528
	ds_read_b128 v[92:95], v64 offset:768
	ds_read_b128 v[96:99], v64 offset:784
	ds_read_b128 v[100:103], v64 offset:1024
	ds_read_b128 v[104:107], v64 offset:1040
	ds_read_b32 v108, v66 offset:24576
	ds_read_b32 v110, v66 offset:24584
	s_waitcnt lgkmcnt(0)
	ds_read_b128 v[112:115], v64 offset:1280
	ds_read_b128 v[116:119], v64 offset:1296
	ds_read_b128 v[120:123], v64 offset:1536
	ds_read_b128 v[124:127], v64 offset:1552
	ds_read_b128 v[128:131], v64 offset:1792
	ds_read_b128 v[132:135], v64 offset:1808
	ds_read_b128 v[136:139], v64 offset:2048
	ds_read_b128 v[140:143], v64 offset:2064
	ds_read_b128 v[144:147], v64 offset:2304
	ds_read_b128 v[148:151], v64 offset:2320
	ds_read_b32 v152, v66 offset:24832
	ds_read_b32 v154, v66 offset:24840
	s_branch .LBB0_511

; __device__ __forceinline__ float red4(float x) { x += dppf(x, 0); x += dppf(x, 1); return x; }
; __device__ __forceinline__ void scan_phase(const Params& p, int j, unsigned char* smem) {
;     ...
;                 const float vv = VB[t * 64 + vrow];
;                 f32x2 s0 = {0.f, 0.f}, s1 = {0.f, 0.f};
; #pragma unroll
;                 for (int i = 0; i < 4; ++i) { s0 += S[2 * i] * (f32x2){A4[i][0], A4[i][1]}; s1 += S[2 * i + 1] * (f32x2){A4[i][2], A4[i][3]}; }
;                 const float sa = red4((s0[0] + s0[1]) + (s1[0] + s1[1]));
;                 const f32x2 sa2 = {sa, sa}, vv2 = {vv, vv};
; #pragma unroll
;                 for (int i = 0; i < 4; ++i) {
;                     S[2 * i] = S[2 * i] * (f32x2){W4[i][0], W4[i][1]} + sa2 * (f32x2){B4[i][0], B4[i][1]} + vv2 * (f32x2){K4[i][0], K4[i][1]};
;                     S[2 * i + 1] = S[2 * i + 1] * (f32x2){W4[i][2], W4[i][3]} + sa2 * (f32x2){B4[i][2], B4[i][3]} + vv2 * (f32x2){K4[i][2], K4[i][3]};
;                 }
;                 f32x2 y0 = {0.f, 0.f}, y1 = {0.f, 0.f};
; #pragma unroll
;                 for (int i = 0; i < 4; ++i) { y0 += S[2 * i] * (f32x2){R4[i][0], R4[i][1]}; y1 += S[2 * i + 1] * (f32x2){R4[i][2], R4[i][3]}; }
;                 const float y = red4((y0[0] + y0[1]) + (y1[0] + y1[1]));
;                 if (kq == 0) YB[t * 64 + vrow] = y;
.LBB0_511:
	v_pk_mul_f32 v[156:157], v[38:39], v[68:69]
	v_pk_mul_f32 v[158:159], v[46:47], v[68:69]
	v_pk_fma_f32 v[156:157], v[40:41], v[70:71], v[156:157]
	v_pk_fma_f32 v[158:159], v[48:49], v[70:71], v[158:159]
	v_pk_fma_f32 v[156:157], v[42:43], v[72:73], v[156:157]
	v_pk_fma_f32 v[158:159], v[50:51], v[72:73], v[158:159]
	v_pk_fma_f32 v[156:157], v[44:45], v[74:75], v[156:157]
	v_pk_fma_f32 v[158:159], v[52:53], v[74:75], v[158:159]
	v_add_f32_e32 v156, v156, v157
	v_add_f32_e32 v158, v158, v159
	v_pk_mul_f32 v[38:39], v[38:39], v[84:85]
	v_add_f32_dpp v168, v156, v156 quad_perm:[1,0,3,2] row_mask:0xf bank_mask:0xf bound_ctrl:1
	v_add_f32_dpp v169, v158, v158 quad_perm:[1,0,3,2] row_mask:0xf bank_mask:0xf bound_ctrl:1
	v_pk_mul_f32 v[46:47], v[46:47], v[84:85]
	v_add_f32_dpp v170, v168, v168 quad_perm:[2,3,0,1] row_mask:0xf bank_mask:0xf bound_ctrl:1
	v_add_f32_dpp v171, v169, v169 quad_perm:[2,3,0,1] row_mask:0xf bank_mask:0xf bound_ctrl:1
	v_pk_mul_f32 v[40:41], v[40:41], v[86:87]
	v_add_f32_dpp v160, v170, v170 row_ror:8 row_mask:0xf bank_mask:0xf
	v_add_f32_dpp v162, v171, v171 row_ror:8 row_mask:0xf bank_mask:0xf
	v_pk_mul_f32 v[48:49], v[48:49], v[86:87]
	v_pk_mul_f32 v[42:43], v[42:43], v[88:89]
	v_pk_mul_f32 v[50:51], v[50:51], v[88:89]
	v_pk_mul_f32 v[44:45], v[44:45], v[90:91]
	v_pk_mul_f32 v[52:53], v[52:53], v[90:91]
	v_pk_fma_f32 v[38:39], v[76:77], v[160:161], v[38:39] op_sel_hi:[1,0,1]
	v_pk_fma_f32 v[46:47], v[76:77], v[162:163], v[46:47] op_sel_hi:[1,0,1]
	v_pk_fma_f32 v[40:41], v[78:79], v[160:161], v[40:41] op_sel_hi:[1,0,1]
	v_pk_fma_f32 v[48:49], v[78:79], v[162:163], v[48:49] op_sel_hi:[1,0,1]
	v_pk_fma_f32 v[42:43], v[80:81], v[160:161], v[42:43] op_sel_hi:[1,0,1]
	v_pk_fma_f32 v[50:51], v[80:81], v[162:163], v[50:51] op_sel_hi:[1,0,1]
	v_pk_fma_f32 v[44:45], v[82:83], v[160:161], v[44:45] op_sel_hi:[1,0,1]
	v_pk_fma_f32 v[52:53], v[82:83], v[162:163], v[52:53] op_sel_hi:[1,0,1]
	v_pk_fma_f32 v[38:39], v[92:93], v[108:109], v[38:39] op_sel_hi:[1,0,1]
	v_pk_fma_f32 v[46:47], v[92:93], v[110:111], v[46:47] op_sel_hi:[1,0,1]
	v_pk_fma_f32 v[40:41], v[94:95], v[108:109], v[40:41] op_sel_hi:[1,0,1]
	v_pk_fma_f32 v[48:49], v[94:95], v[110:111], v[48:49] op_sel_hi:[1,0,1]
	v_pk_fma_f32 v[42:43], v[96:97], v[108:109], v[42:43] op_sel_hi:[1,0,1]
	v_pk_fma_f32 v[50:51], v[96:97], v[110:111], v[50:51] op_sel_hi:[1,0,1]
	v_pk_fma_f32 v[44:45], v[98:99], v[108:109], v[44:45] op_sel_hi:[1,0,1]
	v_pk_fma_f32 v[52:53], v[98:99], v[110:111], v[52:53] op_sel_hi:[1,0,1]
	v_pk_mul_f32 v[164:165], v[38:39], v[100:101]
	v_pk_mul_f32 v[166:167], v[46:47], v[100:101]
	v_pk_fma_f32 v[164:165], v[40:41], v[102:103], v[164:165]
	v_pk_fma_f32 v[166:167], v[48:49], v[102:103], v[166:167]
	v_pk_fma_f32 v[164:165], v[42:43], v[104:105], v[164:165]
	v_pk_fma_f32 v[166:167], v[50:51], v[104:105], v[166:167]
	v_pk_fma_f32 v[164:165], v[44:45], v[106:107], v[164:165]
	v_pk_fma_f32 v[166:167], v[52:53], v[106:107], v[166:167]
	v_add_f32_e32 v164, v164, v165
	v_add_f32_e32 v166, v166, v167
	s_waitcnt lgkmcnt(0)
	ds_read_b128 v[68:71], v64 offset:2560
	v_add_f32_dpp v168, v164, v164 quad_perm:[1,0,3,2] row_mask:0xf bank_mask:0xf bound_ctrl:1
	v_add_f32_dpp v169, v166, v166 quad_perm:[1,0,3,2] row_mask:0xf bank_mask:0xf bound_ctrl:1
	ds_read_b128 v[72:75], v64 offset:2576
	v_add_f32_dpp v170, v168, v168 quad_perm:[2,3,0,1] row_mask:0xf bank_mask:0xf bound_ctrl:1
	v_add_f32_dpp v171, v169, v169 quad_perm:[2,3,0,1] row_mask:0xf bank_mask:0xf bound_ctrl:1
	ds_read_b128 v[76:79], v64 offset:2816
	v_add_f32_dpp v164, v170, v170 row_ror:8 row_mask:0xf bank_mask:0xf
	v_add_f32_dpp v166, v171, v171 row_ror:8 row_mask:0xf bank_mask:0xf
	ds_read_b128 v[80:83], v64 offset:2832
	ds_read_b128 v[84:87], v64 offset:3072
	ds_read_b128 v[88:91], v64 offset:3088
	ds_read_b128 v[92:95], v64 offset:3328
	ds_read_b128 v[96:99], v64 offset:3344
	ds_read_b128 v[100:103], v64 offset:3584
	ds_read_b128 v[104:107], v64 offset:3600
	ds_read_b32 v108, v66 offset:25088
	ds_read_b32 v110, v66 offset:25096
	ds_write_b32 v66, v164 offset:32768
	ds_write_b32 v66, v166 offset:32776
	v_pk_mul_f32 v[156:157], v[38:39], v[112:113]
	v_pk_mul_f32 v[158:159], v[46:47], v[112:113]
	v_pk_fma_f32 v[156:157], v[40:41], v[114:115], v[156:157]
	v_pk_fma_f32 v[158:159], v[48:49], v[114:115], v[158:159]
	v_pk_fma_f32 v[156:157], v[42:43], v[116:117], v[156:157]
	v_pk_fma_f32 v[158:159], v[50:51], v[116:117], v[158:159]
	v_pk_fma_f32 v[156:157], v[44:45], v[118:119], v[156:157]
	v_pk_fma_f32 v[158:159], v[52:53], v[118:119], v[158:159]
	v_add_f32_e32 v156, v156, v157
	v_add_f32_e32 v158, v158, v159
	v_pk_mul_f32 v[38:39], v[38:39], v[128:129]
	v_add_f32_dpp v168, v156, v156 quad_perm:[1,0,3,2] row_mask:0xf bank_mask:0xf bound_ctrl:1
	v_add_f32_dpp v169, v158, v158 quad_perm:[1,0,3,2] row_mask:0xf bank_mask:0xf bound_ctrl:1
	v_pk_mul_f32 v[46:47], v[46:47], v[128:129]
	v_add_f32_dpp v170, v168, v168 quad_perm:[2,3,0,1] row_mask:0xf bank_mask:0xf bound_ctrl:1
	v_add_f32_dpp v171, v169, v169 quad_perm:[2,3,0,1] row_mask:0xf bank_mask:0xf bound_ctrl:1
	v_pk_mul_f32 v[40:41], v[40:41], v[130:131]
	v_add_f32_dpp v160, v170, v170 row_ror:8 row_mask:0xf bank_mask:0xf
	v_add_f32_dpp v162, v171, v171 row_ror:8 row_mask:0xf bank_mask:0xf
	v_pk_mul_f32 v[48:49], v[48:49], v[130:131]
	v_pk_mul_f32 v[42:43], v[42:43], v[132:133]
	v_pk_mul_f32 v[50:51], v[50:51], v[132:133]
	v_pk_mul_f32 v[44:45], v[44:45], v[134:135]
	v_pk_mul_f32 v[52:53], v[52:53], v[134:135]
	v_pk_fma_f32 v[38:39], v[120:121], v[160:161], v[38:39] op_sel_hi:[1,0,1]
	v_pk_fma_f32 v[46:47], v[120:121], v[162:163], v[46:47] op_sel_hi:[1,0,1]
; __device__ __forceinline__ float red4(float x) { x += dppf(x, 0); x += dppf(x, 1); return x; }
; __device__ __forceinline__ void scan_phase(const Params& p, int j, unsigned char* smem) {
;     ...
;             for (int t = 0; t < 16; ++t) {
;                 const float* op = OPS + t * 320 + kq * 16;
;                 f32x4 A4[4], B4[4], W4[4], K4[4], R4[4];
; #pragma unroll
;                 for (int i = 0; i < 4; ++i) A4[i] = *(const f32x4*)(op + i * 4);
; #pragma unroll
;                 for (int i = 0; i < 4; ++i) { W4[i] = *(const f32x4*)(op + 128 + i * 4); B4[i] = *(const f32x4*)(op + 64 + i * 4); K4[i] = *(const f32x4*)(op + 192 + i * 4); }
; #pragma unroll
;                 for (int i = 0; i < 4; ++i) R4[i] = *(const f32x4*)(op + 256 + i * 4);
;                 const float vv = VB[t * 64 + vrow];
;                 f32x2 s0 = {0.f, 0.f}, s1 = {0.f, 0.f};
; #pragma unroll
;                 for (int i = 0; i < 4; ++i) { s0 += S[2 * i] * (f32x2){A4[i][0], A4[i][1]}; s1 += S[2 * i + 1] * (f32x2){A4[i][2], A4[i][3]}; }
;                 const float sa = red4((s0[0] + s0[1]) + (s1[0] + s1[1]));
;                 const f32x2 sa2 = {sa, sa}, vv2 = {vv, vv};
; #pragma unroll
;                 for (int i = 0; i < 4; ++i) {
;                     S[2 * i] = S[2 * i] * (f32x2){W4[i][0], W4[i][1]} + sa2 * (f32x2){B4[i][0], B4[i][1]} + vv2 * (f32x2){K4[i][0], K4[i][1]};
;                     S[2 * i + 1] = S[2 * i + 1] * (f32x2){W4[i][2], W4[i][3]} + sa2 * (f32x2){B4[i][2], B4[i][3]} + vv2 * (f32x2){K4[i][2], K4[i][3]};
;                 }
;                 f32x2 y0 = {0.f, 0.f}, y1 = {0.f, 0.f};
; #pragma unroll
;                 for (int i = 0; i < 4; ++i) { y0 += S[2 * i] * (f32x2){R4[i][0], R4[i][1]}; y1 += S[2 * i + 1] * (f32x2){R4[i][2], R4[i][3]}; }
;                 const float y = red4((y0[0] + y0[1]) + (y1[0] + y1[1]));
;                 if (kq == 0) YB[t * 64 + vrow] = y;
	v_pk_fma_f32 v[40:41], v[122:123], v[160:161], v[40:41] op_sel_hi:[1,0,1]
	v_pk_fma_f32 v[48:49], v[122:123], v[162:163], v[48:49] op_sel_hi:[1,0,1]
	v_pk_fma_f32 v[42:43], v[124:125], v[160:161], v[42:43] op_sel_hi:[1,0,1]
	v_pk_fma_f32 v[50:51], v[124:125], v[162:163], v[50:51] op_sel_hi:[1,0,1]
	v_pk_fma_f32 v[44:45], v[126:127], v[160:161], v[44:45] op_sel_hi:[1,0,1]
	v_pk_fma_f32 v[52:53], v[126:127], v[162:163], v[52:53] op_sel_hi:[1,0,1]
	v_pk_fma_f32 v[38:39], v[136:137], v[152:153], v[38:39] op_sel_hi:[1,0,1]
	v_pk_fma_f32 v[46:47], v[136:137], v[154:155], v[46:47] op_sel_hi:[1,0,1]
	v_pk_fma_f32 v[40:41], v[138:139], v[152:153], v[40:41] op_sel_hi:[1,0,1]
	v_pk_fma_f32 v[48:49], v[138:139], v[154:155], v[48:49] op_sel_hi:[1,0,1]
	v_pk_fma_f32 v[42:43], v[140:141], v[152:153], v[42:43] op_sel_hi:[1,0,1]
	v_pk_fma_f32 v[50:51], v[140:141], v[154:155], v[50:51] op_sel_hi:[1,0,1]
	v_pk_fma_f32 v[44:45], v[142:143], v[152:153], v[44:45] op_sel_hi:[1,0,1]
	v_pk_fma_f32 v[52:53], v[142:143], v[154:155], v[52:53] op_sel_hi:[1,0,1]
	v_pk_mul_f32 v[164:165], v[38:39], v[144:145]
	v_pk_mul_f32 v[166:167], v[46:47], v[144:145]
	v_pk_fma_f32 v[164:165], v[40:41], v[146:147], v[164:165]
	v_pk_fma_f32 v[166:167], v[48:49], v[146:147], v[166:167]
	v_pk_fma_f32 v[164:165], v[42:43], v[148:149], v[164:165]
	v_pk_fma_f32 v[166:167], v[50:51], v[148:149], v[166:167]
	v_pk_fma_f32 v[164:165], v[44:45], v[150:151], v[164:165]
	v_pk_fma_f32 v[166:167], v[52:53], v[150:151], v[166:167]
	v_add_f32_e32 v164, v164, v165
	v_add_f32_e32 v166, v166, v167
	s_waitcnt lgkmcnt(0)
	ds_read_b128 v[112:115], v64 offset:3840
	v_add_f32_dpp v168, v164, v164 quad_perm:[1,0,3,2] row_mask:0xf bank_mask:0xf bound_ctrl:1
	v_add_f32_dpp v169, v166, v166 quad_perm:[1,0,3,2] row_mask:0xf bank_mask:0xf bound_ctrl:1
	ds_read_b128 v[116:119], v64 offset:3856
	v_add_f32_dpp v170, v168, v168 quad_perm:[2,3,0,1] row_mask:0xf bank_mask:0xf bound_ctrl:1
	v_add_f32_dpp v171, v169, v169 quad_perm:[2,3,0,1] row_mask:0xf bank_mask:0xf bound_ctrl:1
	ds_read_b128 v[120:123], v64 offset:4096
	v_add_f32_dpp v164, v170, v170 row_ror:8 row_mask:0xf bank_mask:0xf
	v_add_f32_dpp v166, v171, v171 row_ror:8 row_mask:0xf bank_mask:0xf
	ds_read_b128 v[124:127], v64 offset:4112
	ds_read_b128 v[128:131], v64 offset:4352
	ds_read_b128 v[132:135], v64 offset:4368
	ds_read_b128 v[136:139], v64 offset:4608
	ds_read_b128 v[140:143], v64 offset:4624
	ds_read_b128 v[144:147], v64 offset:4864
	ds_read_b128 v[148:151], v64 offset:4880
	ds_read_b32 v152, v66 offset:25344
	ds_read_b32 v154, v66 offset:25352
	ds_write_b32 v66, v164 offset:33024
	ds_write_b32 v66, v166 offset:33032
	v_pk_mul_f32 v[156:157], v[38:39], v[68:69]
	v_pk_mul_f32 v[158:159], v[46:47], v[68:69]
	v_pk_fma_f32 v[156:157], v[40:41], v[70:71], v[156:157]
	v_pk_fma_f32 v[158:159], v[48:49], v[70:71], v[158:159]
	v_pk_fma_f32 v[156:157], v[42:43], v[72:73], v[156:157]
	v_pk_fma_f32 v[158:159], v[50:51], v[72:73], v[158:159]
	v_pk_fma_f32 v[156:157], v[44:45], v[74:75], v[156:157]
	v_pk_fma_f32 v[158:159], v[52:53], v[74:75], v[158:159]
	v_add_f32_e32 v156, v156, v157
	v_add_f32_e32 v158, v158, v159
	v_pk_mul_f32 v[38:39], v[38:39], v[84:85]
	v_add_f32_dpp v168, v156, v156 quad_perm:[1,0,3,2] row_mask:0xf bank_mask:0xf bound_ctrl:1
	v_add_f32_dpp v169, v158, v158 quad_perm:[1,0,3,2] row_mask:0xf bank_mask:0xf bound_ctrl:1
	v_pk_mul_f32 v[46:47], v[46:47], v[84:85]
	v_add_f32_dpp v170, v168, v168 quad_perm:[2,3,0,1] row_mask:0xf bank_mask:0xf bound_ctrl:1
	v_add_f32_dpp v171, v169, v169 quad_perm:[2,3,0,1] row_mask:0xf bank_mask:0xf bound_ctrl:1
	v_pk_mul_f32 v[40:41], v[40:41], v[86:87]
	v_add_f32_dpp v160, v170, v170 row_ror:8 row_mask:0xf bank_mask:0xf
	v_add_f32_dpp v162, v171, v171 row_ror:8 row_mask:0xf bank_mask:0xf
	v_pk_mul_f32 v[48:49], v[48:49], v[86:87]
	v_pk_mul_f32 v[42:43], v[42:43], v[88:89]
	v_pk_mul_f32 v[50:51], v[50:51], v[88:89]
	v_pk_mul_f32 v[44:45], v[44:45], v[90:91]
	v_pk_mul_f32 v[52:53], v[52:53], v[90:91]
	v_pk_fma_f32 v[38:39], v[76:77], v[160:161], v[38:39] op_sel_hi:[1,0,1]
	v_pk_fma_f32 v[46:47], v[76:77], v[162:163], v[46:47] op_sel_hi:[1,0,1]
	v_pk_fma_f32 v[40:41], v[78:79], v[160:161], v[40:41] op_sel_hi:[1,0,1]
	v_pk_fma_f32 v[48:49], v[78:79], v[162:163], v[48:49] op_sel_hi:[1,0,1]
	v_pk_fma_f32 v[42:43], v[80:81], v[160:161], v[42:43] op_sel_hi:[1,0,1]
	v_pk_fma_f32 v[50:51], v[80:81], v[162:163], v[50:51] op_sel_hi:[1,0,1]
	v_pk_fma_f32 v[44:45], v[82:83], v[160:161], v[44:45] op_sel_hi:[1,0,1]
	v_pk_fma_f32 v[52:53], v[82:83], v[162:163], v[52:53] op_sel_hi:[1,0,1]
	v_pk_fma_f32 v[38:39], v[92:93], v[108:109], v[38:39] op_sel_hi:[1,0,1]
	v_pk_fma_f32 v[46:47], v[92:93], v[110:111], v[46:47] op_sel_hi:[1,0,1]
	v_pk_fma_f32 v[40:41], v[94:95], v[108:109], v[40:41] op_sel_hi:[1,0,1]
	v_pk_fma_f32 v[48:49], v[94:95], v[110:111], v[48:49] op_sel_hi:[1,0,1]
	v_pk_fma_f32 v[42:43], v[96:97], v[108:109], v[42:43] op_sel_hi:[1,0,1]
	v_pk_fma_f32 v[50:51], v[96:97], v[110:111], v[50:51] op_sel_hi:[1,0,1]
	v_pk_fma_f32 v[44:45], v[98:99], v[108:109], v[44:45] op_sel_hi:[1,0,1]
	v_pk_fma_f32 v[52:53], v[98:99], v[110:111], v[52:53] op_sel_hi:[1,0,1]
	v_pk_mul_f32 v[164:165], v[38:39], v[100:101]
	v_pk_mul_f32 v[166:167], v[46:47], v[100:101]
	v_pk_fma_f32 v[164:165], v[40:41], v[102:103], v[164:165]
	v_pk_fma_f32 v[166:167], v[48:49], v[102:103], v[166:167]
	v_pk_fma_f32 v[164:165], v[42:43], v[104:105], v[164:165]
	v_pk_fma_f32 v[166:167], v[50:51], v[104:105], v[166:167]
	v_pk_fma_f32 v[164:165], v[44:45], v[106:107], v[164:165]
	v_pk_fma_f32 v[166:167], v[52:53], v[106:107], v[166:167]
	v_add_f32_e32 v164, v164, v165
	v_add_f32_e32 v166, v166, v167
	s_waitcnt lgkmcnt(0)
; __device__ __forceinline__ float red4(float x) { x += dppf(x, 0); x += dppf(x, 1); return x; }
; __device__ __forceinline__ void scan_phase(const Params& p, int j, unsigned char* smem) {
;     ...
;             for (int t = 0; t < 16; ++t) {
;                 const float* op = OPS + t * 320 + kq * 16;
;                 f32x4 A4[4], B4[4], W4[4], K4[4], R4[4];
; #pragma unroll
;                 for (int i = 0; i < 4; ++i) A4[i] = *(const f32x4*)(op + i * 4);
; #pragma unroll
;                 for (int i = 0; i < 4; ++i) { W4[i] = *(const f32x4*)(op + 128 + i * 4); B4[i] = *(const f32x4*)(op + 64 + i * 4); K4[i] = *(const f32x4*)(op + 192 + i * 4); }
; #pragma unroll
;                 for (int i = 0; i < 4; ++i) R4[i] = *(const f32x4*)(op + 256 + i * 4);
;                 const float vv = VB[t * 64 + vrow];
;                 f32x2 s0 = {0.f, 0.f}, s1 = {0.f, 0.f};
; #pragma unroll
;                 for (int i = 0; i < 4; ++i) { s0 += S[2 * i] * (f32x2){A4[i][0], A4[i][1]}; s1 += S[2 * i + 1] * (f32x2){A4[i][2], A4[i][3]}; }
;                 const float sa = red4((s0[0] + s0[1]) + (s1[0] + s1[1]));
;                 const f32x2 sa2 = {sa, sa}, vv2 = {vv, vv};
; #pragma unroll
;                 for (int i = 0; i < 4; ++i) {
;                     S[2 * i] = S[2 * i] * (f32x2){W4[i][0], W4[i][1]} + sa2 * (f32x2){B4[i][0], B4[i][1]} + vv2 * (f32x2){K4[i][0], K4[i][1]};
;                     S[2 * i + 1] = S[2 * i + 1] * (f32x2){W4[i][2], W4[i][3]} + sa2 * (f32x2){B4[i][2], B4[i][3]} + vv2 * (f32x2){K4[i][2], K4[i][3]};
;                 }
;                 f32x2 y0 = {0.f, 0.f}, y1 = {0.f, 0.f};
; #pragma unroll
;                 for (int i = 0; i < 4; ++i) { y0 += S[2 * i] * (f32x2){R4[i][0], R4[i][1]}; y1 += S[2 * i + 1] * (f32x2){R4[i][2], R4[i][3]}; }
;                 const float y = red4((y0[0] + y0[1]) + (y1[0] + y1[1]));
;                 if (kq == 0) YB[t * 64 + vrow] = y;
	ds_read_b128 v[68:71], v64 offset:5120
	v_add_f32_dpp v168, v164, v164 quad_perm:[1,0,3,2] row_mask:0xf bank_mask:0xf bound_ctrl:1
	v_add_f32_dpp v169, v166, v166 quad_perm:[1,0,3,2] row_mask:0xf bank_mask:0xf bound_ctrl:1
	ds_read_b128 v[72:75], v64 offset:5136
	v_add_f32_dpp v170, v168, v168 quad_perm:[2,3,0,1] row_mask:0xf bank_mask:0xf bound_ctrl:1
	v_add_f32_dpp v171, v169, v169 quad_perm:[2,3,0,1] row_mask:0xf bank_mask:0xf bound_ctrl:1
	ds_read_b128 v[76:79], v64 offset:5376
	v_add_f32_dpp v164, v170, v170 row_ror:8 row_mask:0xf bank_mask:0xf
	v_add_f32_dpp v166, v171, v171 row_ror:8 row_mask:0xf bank_mask:0xf
	ds_read_b128 v[80:83], v64 offset:5392
	ds_read_b128 v[84:87], v64 offset:5632
	ds_read_b128 v[88:91], v64 offset:5648
	ds_read_b128 v[92:95], v64 offset:5888
	ds_read_b128 v[96:99], v64 offset:5904
	ds_read_b128 v[100:103], v64 offset:6144
	ds_read_b128 v[104:107], v64 offset:6160
	ds_read_b32 v108, v66 offset:25600
	ds_read_b32 v110, v66 offset:25608
	ds_write_b32 v66, v164 offset:33280
	ds_write_b32 v66, v166 offset:33288
	v_pk_mul_f32 v[156:157], v[38:39], v[112:113]
	v_pk_mul_f32 v[158:159], v[46:47], v[112:113]
	v_pk_fma_f32 v[156:157], v[40:41], v[114:115], v[156:157]
	v_pk_fma_f32 v[158:159], v[48:49], v[114:115], v[158:159]
	v_pk_fma_f32 v[156:157], v[42:43], v[116:117], v[156:157]
	v_pk_fma_f32 v[158:159], v[50:51], v[116:117], v[158:159]
	v_pk_fma_f32 v[156:157], v[44:45], v[118:119], v[156:157]
	v_pk_fma_f32 v[158:159], v[52:53], v[118:119], v[158:159]
	v_add_f32_e32 v156, v156, v157
	v_add_f32_e32 v158, v158, v159
	v_pk_mul_f32 v[38:39], v[38:39], v[128:129]
	v_add_f32_dpp v168, v156, v156 quad_perm:[1,0,3,2] row_mask:0xf bank_mask:0xf bound_ctrl:1
	v_add_f32_dpp v169, v158, v158 quad_perm:[1,0,3,2] row_mask:0xf bank_mask:0xf bound_ctrl:1
	v_pk_mul_f32 v[46:47], v[46:47], v[128:129]
	v_add_f32_dpp v170, v168, v168 quad_perm:[2,3,0,1] row_mask:0xf bank_mask:0xf bound_ctrl:1
	v_add_f32_dpp v171, v169, v169 quad_perm:[2,3,0,1] row_mask:0xf bank_mask:0xf bound_ctrl:1
	v_pk_mul_f32 v[40:41], v[40:41], v[130:131]
	v_add_f32_dpp v160, v170, v170 row_ror:8 row_mask:0xf bank_mask:0xf
	v_add_f32_dpp v162, v171, v171 row_ror:8 row_mask:0xf bank_mask:0xf
	v_pk_mul_f32 v[48:49], v[48:49], v[130:131]
	v_pk_mul_f32 v[42:43], v[42:43], v[132:133]
	v_pk_mul_f32 v[50:51], v[50:51], v[132:133]
	v_pk_mul_f32 v[44:45], v[44:45], v[134:135]
	v_pk_mul_f32 v[52:53], v[52:53], v[134:135]
	v_pk_fma_f32 v[38:39], v[120:121], v[160:161], v[38:39] op_sel_hi:[1,0,1]
	v_pk_fma_f32 v[46:47], v[120:121], v[162:163], v[46:47] op_sel_hi:[1,0,1]
	v_pk_fma_f32 v[40:41], v[122:123], v[160:161], v[40:41] op_sel_hi:[1,0,1]
	v_pk_fma_f32 v[48:49], v[122:123], v[162:163], v[48:49] op_sel_hi:[1,0,1]
	v_pk_fma_f32 v[42:43], v[124:125], v[160:161], v[42:43] op_sel_hi:[1,0,1]
	v_pk_fma_f32 v[50:51], v[124:125], v[162:163], v[50:51] op_sel_hi:[1,0,1]
	v_pk_fma_f32 v[44:45], v[126:127], v[160:161], v[44:45] op_sel_hi:[1,0,1]
	v_pk_fma_f32 v[52:53], v[126:127], v[162:163], v[52:53] op_sel_hi:[1,0,1]
	v_pk_fma_f32 v[38:39], v[136:137], v[152:153], v[38:39] op_sel_hi:[1,0,1]
	v_pk_fma_f32 v[46:47], v[136:137], v[154:155], v[46:47] op_sel_hi:[1,0,1]
	v_pk_fma_f32 v[40:41], v[138:139], v[152:153], v[40:41] op_sel_hi:[1,0,1]
	v_pk_fma_f32 v[48:49], v[138:139], v[154:155], v[48:49] op_sel_hi:[1,0,1]
	v_pk_fma_f32 v[42:43], v[140:141], v[152:153], v[42:43] op_sel_hi:[1,0,1]
	v_pk_fma_f32 v[50:51], v[140:141], v[154:155], v[50:51] op_sel_hi:[1,0,1]
	v_pk_fma_f32 v[44:45], v[142:143], v[152:153], v[44:45] op_sel_hi:[1,0,1]
	v_pk_fma_f32 v[52:53], v[142:143], v[154:155], v[52:53] op_sel_hi:[1,0,1]
	v_pk_mul_f32 v[164:165], v[38:39], v[144:145]
	v_pk_mul_f32 v[166:167], v[46:47], v[144:145]
	v_pk_fma_f32 v[164:165], v[40:41], v[146:147], v[164:165]
	v_pk_fma_f32 v[166:167], v[48:49], v[146:147], v[166:167]
	v_pk_fma_f32 v[164:165], v[42:43], v[148:149], v[164:165]
	v_pk_fma_f32 v[166:167], v[50:51], v[148:149], v[166:167]
	v_pk_fma_f32 v[164:165], v[44:45], v[150:151], v[164:165]
	v_pk_fma_f32 v[166:167], v[52:53], v[150:151], v[166:167]
	v_add_f32_e32 v164, v164, v165
	v_add_f32_e32 v166, v166, v167
	s_waitcnt lgkmcnt(0)
	ds_read_b128 v[112:115], v64 offset:6400
	v_add_f32_dpp v168, v164, v164 quad_perm:[1,0,3,2] row_mask:0xf bank_mask:0xf bound_ctrl:1
	v_add_f32_dpp v169, v166, v166 quad_perm:[1,0,3,2] row_mask:0xf bank_mask:0xf bound_ctrl:1
	ds_read_b128 v[116:119], v64 offset:6416
	v_add_f32_dpp v170, v168, v168 quad_perm:[2,3,0,1] row_mask:0xf bank_mask:0xf bound_ctrl:1
	v_add_f32_dpp v171, v169, v169 quad_perm:[2,3,0,1] row_mask:0xf bank_mask:0xf bound_ctrl:1
	ds_read_b128 v[120:123], v64 offset:6656
	v_add_f32_dpp v164, v170, v170 row_ror:8 row_mask:0xf bank_mask:0xf
	v_add_f32_dpp v166, v171, v171 row_ror:8 row_mask:0xf bank_mask:0xf
	ds_read_b128 v[124:127], v64 offset:6672
	ds_read_b128 v[128:131], v64 offset:6912
	ds_read_b128 v[132:135], v64 offset:6928
	ds_read_b128 v[136:139], v64 offset:7168
	ds_read_b128 v[140:143], v64 offset:7184
	ds_read_b128 v[144:147], v64 offset:7424
	ds_read_b128 v[148:151], v64 offset:7440
	ds_read_b32 v152, v66 offset:25856
	ds_read_b32 v154, v66 offset:25864
	ds_write_b32 v66, v164 offset:33536
	ds_write_b32 v66, v166 offset:33544
	s_branch .LBB0_510

; __device__ __forceinline__ void gemm_phase(LAS unsigned char* lds, const Gemm g, const StaticOrder& S, const Epi& E) {
;     ...
;     for (int i = 0; i < 2; ++i) { int R, C; stage_rc(tid * 16 + i * 8192, R, C); const int Rb = (R & ~31) + perm32(R & 31);
;         voffA[i] = (unsigned)(R * g.lda + C) * 2u; voffB[i] = (unsigned)(Rb * K + C) * 2u; }
.LBB0_737:
	v_bfe_i32 v2, v12, 27, 1
	v_lshlrev_b32_e32 v0, 4, v12
	v_lshrrev_b32_e32 v2, 22, v2
	v_add_u32_e32 v2, v0, v2
	v_and_b32_e32 v2, 0xfffffc00, v2
	v_ashrrev_i32_e32 v1, 31, v12
	v_sub_u32_e32 v2, v0, v2
	v_lshrrev_b32_e32 v1, 26, v1
	v_lshrrev_b32_e32 v3, 4, v2
	v_add_u32_e32 v1, v12, v1
	v_bitop3_b32 v3, v3, v2, 32 bitop3:0x6c
	v_ashrrev_i32_e32 v2, 31, v2
	v_ashrrev_i32_e32 v1, 6, v1
	v_lshrrev_b32_e32 v2, 26, v2
	v_lshlrev_b32_e32 v4, 3, v1
	v_add_u32_e32 v2, v3, v2
	v_and_b32_e32 v4, -16, v4
	v_ashrrev_i32_e32 v2, 6, v2
	v_lshlrev_b32_e32 v1, 5, v1
	v_add_u32_e32 v4, v2, v4
	v_and_b32_e32 v13, 32, v1
	v_mul_i32_i24_e32 v1, 64, v2
	v_sub_u32_e32 v1, v3, v1
	v_lshlrev_b32_e32 v3, 1, v4
	v_lshrrev_b32_e32 v5, 2, v4
	v_and_b32_e32 v2, 3, v2
	s_mov_b32 s1, 0x7fffffe0
	v_ashrrev_i16_sdwa v1, v227, sext(v1) dst_sel:DWORD dst_unused:UNUSED_PAD src0_sel:DWORD src1_sel:BYTE_0
	v_and_b32_e32 v3, 24, v3
	v_and_b32_e32 v5, 4, v5
	v_and_or_b32 v2, v4, s1, v2
	v_bfe_i32 v14, v1, 0, 16
	v_or3_b32 v2, v2, v5, v3
	v_add_u32_e32 v1, v13, v14
	v_and_b32_e32 v19, 15, v4
	v_bfe_u32 v20, v4, 4, 2
	v_lshl_or_b32 v19, v19, 2, v20
	v_and_b32_e32 v21, 0xffffffc0, v4
	v_or_b32_e32 v19, v21, v19
	s_cmp_eq_u32 s93, 3
	s_cselect_b64 vcc, -1, 0
	s_nop 1
	v_cndmask_b32_e32 v19, v4, v19, vcc
	v_mul_lo_u32 v15, v19, s50
	v_mul_lo_u32 v2, v2, s0
	v_add_u32_e32 v0, 0x2000, v0
	v_add_lshl_u32 v204, v1, v15, 1
	v_add_lshl_u32 v206, v2, v1, 1
	v_ashrrev_i32_e32 v1, 31, v0
	v_lshrrev_b32_e32 v1, 22, v1
	v_add_u32_e32 v1, v0, v1
	v_ashrrev_i32_e32 v1, 10, v1
	v_mul_i32_i24_e32 v2, 0x400, v1
	v_sub_u32_e32 v0, v0, v2
	v_lshrrev_b32_e32 v2, 4, v0
	v_bitop3_b32 v0, v2, v0, 32 bitop3:0x6c
	v_ashrrev_i32_e32 v3, 31, v0
	v_lshrrev_b32_e32 v3, 26, v3
	v_lshlrev_b32_e32 v2, 3, v1
	v_add_u32_e32 v3, v0, v3
	v_and_b32_e32 v2, -16, v2
	v_ashrrev_i32_e32 v4, 6, v3
	v_add_u32_e32 v2, v4, v2
	v_and_b32_e32 v4, 3, v4
	v_and_or_b32 v4, v2, s1, v4
	s_mov_b32 s1, s51
	s_lshl_b64 s[18:19], s[0:1], 8
	s_lshl_b64 s[20:21], s[0:1], 9
	s_ashr_i32 s1, s84, 31
	s_mul_i32 s1, s20, s1
	s_mul_hi_u32 s22, s20, s84
	v_lshlrev_b32_e32 v1, 5, v1
	s_add_i32 s1, s22, s1
	s_lshr_b32 s22, s0, 23
	s_waitcnt vmcnt(0)
	v_and_b32_e32 v16, 32, v1
	v_and_b32_e32 v1, 0xc0, v3
	s_ashr_i32 s24, s57, 6
	s_mul_i32 s22, s22, s84
	s_ashr_i32 s15, s57, 8
	v_sub_u32_e32 v0, v0, v1
	v_lshlrev_b32_e32 v1, 1, v2
	v_lshrrev_b32_e32 v3, 2, v2
	s_lshl_b64 s[16:17], s[50:51], 8
	s_lshl_b32 s31, s24, 10
	s_add_i32 s1, s1, s22
	s_mul_i32 s22, s20, s84
	v_ashrrev_i16_sdwa v0, v227, sext(v0) dst_sel:DWORD dst_unused:UNUSED_PAD src0_sel:DWORD src1_sel:BYTE_0
	v_and_b32_e32 v1, 24, v1
	v_and_b32_e32 v3, 4, v3
	s_add_u32 s36, s10, s22
	v_bfe_i32 v17, v0, 0, 16
	v_or3_b32 v1, v4, v3, v1
	s_addc_u32 s37, s11, s1
	s_add_i32 s58, s31, 0
	v_add_u32_e32 v0, v16, v17
	v_mul_lo_u32 v1, v1, s0
	s_add_i32 m0, s58, 0x10000
	v_add_lshl_u32 v210, v1, v0, 1
	global_load_lds_dwordx4 v206, s[36:37]
	s_add_i32 m0, s58, 0x12000
	v_and_b32_e32 v19, 15, v2
	v_bfe_u32 v20, v2, 4, 2
	v_lshl_or_b32 v19, v19, 2, v20
	v_and_b32_e32 v21, 0xffffffc0, v2
	v_or_b32_e32 v19, v21, v19
	s_cmp_eq_u32 s93, 3
	s_cselect_b64 vcc, -1, 0
	s_nop 1
	v_cndmask_b32_e32 v19, v2, v19, vcc
	v_mul_lo_u32 v18, v19, s50
	global_load_lds_dwordx4 v210, s[36:37]
	s_mov_b32 m0, s58
	s_add_i32 s59, s58, 0x2000
	v_add_lshl_u32 v208, v0, v18, 1
	global_load_lds_dwordx4 v204, s[34:35]
	s_mov_b32 m0, s59
	s_add_u32 s22, s36, s18
	global_load_lds_dwordx4 v208, s[34:35]
	s_addc_u32 s23, s37, s19
	s_add_i32 m0, s58, 0x14000
	v_mov_b32_e32 v207, v197
	global_load_lds_dwordx4 v206, s[22:23]
	s_add_i32 m0, s58, 0x16000
	s_add_u32 s28, s34, s16
	s_addc_u32 s29, s35, s17
	s_add_i32 s60, s58, 0x4000
	global_load_lds_dwordx4 v210, s[22:23]
	s_mov_b32 m0, s60
	s_add_i32 s61, s58, 0x6000
	global_load_lds_dwordx4 v204, s[28:29]
	s_mov_b32 m0, s61
	v_mov_b32_e32 v211, v197
	global_load_lds_dwordx4 v208, s[28:29]
	v_mov_b32_e32 v205, v197
	v_mov_b32_e32 v209, v197
	v_lshl_add_u64 v[10:11], s[36:37], 0, v[206:207]
	v_lshl_add_u64 v[8:9], s[36:37], 0, v[210:211]
	v_lshl_add_u64 v[6:7], s[34:35], 0, v[204:205]
	v_lshl_add_u64 v[4:5], s[34:35], 0, v[208:209]
	v_lshl_add_u64 v[2:3], s[22:23], 0, v[206:207]
	s_cmp_lg_u32 s15, 1
	v_lshl_add_u64 v[0:1], s[22:23], 0, v[210:211]
	s_cbranch_scc1 .LBB0_739
	s_barrier

; __device__ __forceinline__ u32x4 pack8(f32x4 a, f32x4 b) { u32x4 w; w.x = pk2(a[0], a[1]); w.y = pk2(a[2], a[3]); w.z = pk2(b[0], b[1]); w.w = pk2(b[2], b[3]); return w; }
;     __device__ __forceinline__ void operator()(const f32x4 (&acc)[2][2][4][2], const Unit& u, int wr, int wc, int fr, int fq) const {
;     ...
;                     } else if (mode == E_ST16) {
;                         *(u32x4*)((h16*)(ws + F_U16) + (size_t)rowl * 5632 + col) = pack8(v0, v1);
; __device__ __forceinline__ void conv_phase(const Params& p, int layer) {
;     ...
;         float wg[3][8], wv[3][8], bg[8], bv[8];
; #pragma unroll
;         for (int jj = 0; jj < 3; ++jj)
; #pragma unroll
;             for (int hlf = 0; hlf < 2; ++hlf) {
;                 const f32x4 a = *(const f32x4*)(cw + jj * 5632 + f + hlf * 4), c = *(const f32x4*)(cw + jj * 5632 + DFF + f + hlf * 4);
; #pragma unroll
;                 for (int e = 0; e < 4; ++e) { wg[jj][hlf * 4 + e] = a[e]; wv[jj][hlf * 4 + e] = c[e]; }
;             }
; #pragma unroll
;         for (int hlf = 0; hlf < 2; ++hlf) {
;             const f32x4 a = *(const f32x4*)(cb + f + hlf * 4), c = *(const f32x4*)(cb + DFF + f + hlf * 4);
; #pragma unroll
;             for (int e = 0; e < 4; ++e) { bg[hlf * 4 + e] = a[e]; bv[hlf * 4 + e] = c[e]; }
;         }
.Lst16_fast:
	v_readlane_b32 s0, v253, 32
	v_readlane_b32 s1, v253, 33
	v_readlane_b32 s86, v253, 20
	v_readlane_b32 s87, v253, 21
	s_lshl_b32 s27, s84, 7
	s_add_i32 s27, s27, s65
	v_add_u32_e32 v216, s27, v202
	v_lshlrev_b32_e32 v216, 2, v216
	v_add_u32_e32 v217, 0x2c00, v216
	v_add_u32_e32 v218, 0x5800, v216
	v_add_u32_e32 v219, 0x8400, v216
	v_add_u32_e32 v220, 0xb000, v216
	v_add_u32_e32 v221, 0xdc00, v216
	v_mov_b32_e32 v222, v216
	v_add_u32_e32 v223, 0x2c00, v216
	global_load_dwordx4 v[140:143], v222, s[86:87]
	global_load_dwordx4 v[156:159], v223, s[86:87]
	global_load_dwordx4 v[128:131], v216, s[0:1]
	global_load_dwordx4 v[144:147], v217, s[0:1]
	global_load_dwordx4 v[132:135], v218, s[0:1]
	global_load_dwordx4 v[148:151], v219, s[0:1]
	global_load_dwordx4 v[136:139], v220, s[0:1]
	global_load_dwordx4 v[152:155], v221, s[0:1]
	v_readlane_b32 s34, v251, 1
	v_readlane_b32 s35, v251, 2
	s_movk_i32 s33, 0x2c00
	s_lshl_b32 s27, s27, 1
	v_and_b32_e32 v160, 15, v240
	v_lshrrev_b32_e32 v161, 6, v240
	v_lshlrev_b32_e32 v161, 2, v161
	v_lshl_add_u32 v164, v202, 1, s27
	v_mov_b32_e32 v165, v197
	v_mad_u64_u32 v[166:167], s[86:87], v161, s33, v[164:165]
	s_movk_i32 s36, 0x1600
	s_mov_b32 s37, 0
	v_lshl_add_u64 v[166:167], s[34:35], 0, v[166:167]
	s_mov_b32 s34, 0xc600
	s_mov_b32 s35, 0
	v_cmp_eq_u32_e32 vcc, 0, v160
	v_cmp_eq_u32_e64 s[0:1], 15, v160
	s_mov_b64 s[38:39], exec
	v_cvt_pk_f16_f32 v176, v124, v125
	v_cvt_pk_f16_f32 v177, v126, v127
	v_cvt_pk_f16_f32 v178, v120, v121
	v_cvt_pk_f16_f32 v179, v122, v123
	v_lshl_add_u64 v[168:169], v[166:167], 0, s[36:37]
	s_and_b64 exec, s[38:39], vcc
	global_store_dwordx4 v[166:167], v[176:179], off
	s_mov_b64 exec, s[38:39]
	v_cvt_pk_f16_f32 v180, v116, v117
	v_cvt_pk_f16_f32 v181, v118, v119
	v_cvt_pk_f16_f32 v182, v112, v113
	v_cvt_pk_f16_f32 v183, v114, v115
	v_lshl_add_u64 v[166:167], v[168:169], 0, s[36:37]
	s_and_b64 exec, s[38:39], vcc
	global_store_dwordx4 v[168:169], v[180:183], off
	s_mov_b64 exec, s[38:39]
	v_cvt_pk_f16_f32 v184, v108, v109
	v_cvt_pk_f16_f32 v185, v110, v111
	v_cvt_pk_f16_f32 v186, v104, v105
	v_cvt_pk_f16_f32 v187, v106, v107
	v_lshl_add_u64 v[168:169], v[166:167], 0, s[36:37]
	s_and_b64 exec, s[38:39], vcc
	global_store_dwordx4 v[166:167], v[184:187], off
	s_mov_b64 exec, s[38:39]
	v_cvt_pk_f16_f32 v188, v100, v101
	v_cvt_pk_f16_f32 v189, v102, v103
	v_cvt_pk_f16_f32 v190, v96, v97
	v_cvt_pk_f16_f32 v191, v98, v99
	v_lshl_add_u64 v[166:167], v[168:169], 0, s[36:37]
	s_and_b64 exec, s[38:39], vcc
	global_store_dwordx4 v[168:169], v[188:191], off
	s_mov_b64 exec, s[38:39]
	v_cvt_pk_f16_f32 v176, v92, v93
	v_cvt_pk_f16_f32 v177, v94, v95
	v_cvt_pk_f16_f32 v178, v88, v89
	v_cvt_pk_f16_f32 v179, v90, v91
	v_lshl_add_u64 v[168:169], v[166:167], 0, s[36:37]
	s_and_b64 exec, s[38:39], s[0:1]
	global_store_dwordx4 v[166:167], v[176:179], off
	s_mov_b64 exec, s[38:39]
	v_cvt_pk_f16_f32 v180, v84, v85
	v_cvt_pk_f16_f32 v181, v86, v87
	v_cvt_pk_f16_f32 v182, v80, v81
	v_cvt_pk_f16_f32 v183, v82, v83
	v_lshl_add_u64 v[166:167], v[168:169], 0, s[36:37]
	s_and_b64 exec, s[38:39], s[0:1]
	global_store_dwordx4 v[168:169], v[180:183], off
	s_mov_b64 exec, s[38:39]
	v_cvt_pk_f16_f32 v184, v76, v77
	v_cvt_pk_f16_f32 v185, v78, v79
	v_cvt_pk_f16_f32 v186, v72, v73
	v_cvt_pk_f16_f32 v187, v74, v75
	v_lshl_add_u64 v[168:169], v[166:167], 0, s[36:37]
	s_and_b64 exec, s[38:39], s[0:1]
	global_store_dwordx4 v[166:167], v[184:187], off
	s_mov_b64 exec, s[38:39]
	v_cvt_pk_f16_f32 v188, v68, v69
	v_cvt_pk_f16_f32 v189, v70, v71
	v_cvt_pk_f16_f32 v190, v64, v65
	v_cvt_pk_f16_f32 v191, v66, v67
	v_lshl_add_u64 v[166:167], v[168:169], 0, s[34:35]
	s_and_b64 exec, s[38:39], s[0:1]
	global_store_dwordx4 v[168:169], v[188:191], off
	s_mov_b64 exec, s[38:39]
	v_cvt_pk_f16_f32 v176, v60, v61
	v_cvt_pk_f16_f32 v177, v62, v63
	v_cvt_pk_f16_f32 v178, v56, v57
	v_cvt_pk_f16_f32 v179, v58, v59
	v_lshl_add_u64 v[168:169], v[166:167], 0, s[36:37]
	s_and_b64 exec, s[38:39], vcc
	global_store_dwordx4 v[166:167], v[176:179], off
	s_mov_b64 exec, s[38:39]
	v_cvt_pk_f16_f32 v180, v52, v53
	v_cvt_pk_f16_f32 v181, v54, v55
	v_cvt_pk_f16_f32 v182, v48, v49
	v_cvt_pk_f16_f32 v183, v50, v51
	v_lshl_add_u64 v[166:167], v[168:169], 0, s[36:37]
	s_and_b64 exec, s[38:39], vcc
	global_store_dwordx4 v[168:169], v[180:183], off
	s_mov_b64 exec, s[38:39]
	v_cvt_pk_f16_f32 v184, v44, v45
	v_cvt_pk_f16_f32 v185, v46, v47
	v_cvt_pk_f16_f32 v186, v40, v41
	v_cvt_pk_f16_f32 v187, v42, v43
	v_lshl_add_u64 v[168:169], v[166:167], 0, s[36:37]
	s_and_b64 exec, s[38:39], vcc
	global_store_dwordx4 v[166:167], v[184:187], off
	s_mov_b64 exec, s[38:39]
	v_cvt_pk_f16_f32 v188, v36, v37
	v_cvt_pk_f16_f32 v189, v38, v39
	v_cvt_pk_f16_f32 v190, v32, v33
	v_cvt_pk_f16_f32 v191, v34, v35
	v_lshl_add_u64 v[166:167], v[168:169], 0, s[36:37]
	s_and_b64 exec, s[38:39], vcc
	global_store_dwordx4 v[168:169], v[188:191], off
	s_mov_b64 exec, s[38:39]
	v_cvt_pk_f16_f32 v176, v28, v29
	v_cvt_pk_f16_f32 v177, v30, v31
	v_cvt_pk_f16_f32 v178, v24, v25
	v_cvt_pk_f16_f32 v179, v26, v27
	v_lshl_add_u64 v[168:169], v[166:167], 0, s[36:37]
	s_and_b64 exec, s[38:39], s[0:1]
	global_store_dwordx4 v[166:167], v[176:179], off
	s_mov_b64 exec, s[38:39]
	v_cvt_pk_f16_f32 v180, v20, v21
	v_cvt_pk_f16_f32 v181, v22, v23
	v_cvt_pk_f16_f32 v182, v16, v17
	v_cvt_pk_f16_f32 v183, v18, v19
	v_lshl_add_u64 v[166:167], v[168:169], 0, s[36:37]
	s_and_b64 exec, s[38:39], s[0:1]
	global_store_dwordx4 v[168:169], v[180:183], off
	s_mov_b64 exec, s[38:39]
	v_cvt_pk_f16_f32 v184, v12, v13
	v_cvt_pk_f16_f32 v185, v14, v15
	v_cvt_pk_f16_f32 v186, v8, v9
	v_cvt_pk_f16_f32 v187, v10, v11
	v_lshl_add_u64 v[168:169], v[166:167], 0, s[36:37]
	s_and_b64 exec, s[38:39], s[0:1]
	global_store_dwordx4 v[166:167], v[184:187], off
	s_mov_b64 exec, s[38:39]
	v_cvt_pk_f16_f32 v188, v4, v5
	v_cvt_pk_f16_f32 v189, v6, v7
	v_cvt_pk_f16_f32 v190, v0, v1
	v_cvt_pk_f16_f32 v191, v2, v3
	s_and_b64 exec, s[38:39], s[0:1]
	global_store_dwordx4 v[168:169], v[188:191], off
	s_mov_b64 exec, s[38:39]
	s_mov_b64 exec, s[38:39]
	v_readlane_b32 s0, v253, 32
	v_readlane_b32 s1, v253, 33
	v_readlane_b32 s86, v253, 20
	v_readlane_b32 s87, v253, 21
	s_mov_b32 s34, 0xbfb8aa3b
	s_mov_b32 s35, 0xbfb8aa3b
	s_mov_b32 s36, 1.0
	s_mov_b32 s37, 1.0
	s_nop 4
	global_load_dwordx4 v[172:175], v222, s[86:87] offset:16
	global_load_dwordx4 v[188:191], v223, s[86:87] offset:16
	global_load_dwordx4 v[160:163], v216, s[0:1] offset:16
	global_load_dwordx4 v[176:179], v217, s[0:1] offset:16
	global_load_dwordx4 v[164:167], v218, s[0:1] offset:16
	global_load_dwordx4 v[180:183], v219, s[0:1] offset:16
	global_load_dwordx4 v[168:171], v220, s[0:1] offset:16
	global_load_dwordx4 v[184:187], v221, s[0:1] offset:16
	s_waitcnt vmcnt(24)
; __device__ __forceinline__ float sigmoidf_(float x) { return __builtin_amdgcn_rcpf(1.0f + __expf(-x)); }
; __device__ __forceinline__ void conv_phase(const Params& p, int layer) {
;     ...
;                 for (int e = 0; e < 8; ++e) {
;                     const float G = wg[0][e] * g2[e] + wg[1][e] * g1[e] + wg[2][e] * g0[e] + bg[e];
;                     const float V = wv[0][e] * v2[e] + wv[1][e] * v1[e] + wv[2][e] * v0[e] + bv[e];
;                     o[e] = G * sigmoidf_(G) * V;
;                     g2[e] = g1[e]; g1[e] = g0[e]; v2[e] = v1[e]; v1[e] = v0[e];
;                 }
	v_pk_fma_f32 v[192:193], v[124:125], v[136:137], v[140:141]
	v_pk_fma_f32 v[216:217], v[116:117], v[152:153], v[156:157]
	v_pk_fma_f32 v[194:195], v[108:109], v[136:137], v[140:141]
	v_pk_fma_f32 v[218:219], v[100:101], v[152:153], v[156:157]
	v_fmac_f32_dpp v192, v76, v132 row_shr:1 row_mask:0xf bank_mask:0xf
	v_fmac_f32_dpp v216, v68, v148 row_shr:1 row_mask:0xf bank_mask:0xf
	v_pk_fma_f32 v[194:195], v[124:125], v[132:133], v[194:195]
	v_pk_fma_f32 v[218:219], v[116:117], v[148:149], v[218:219]
	v_fmac_f32_dpp v193, v77, v133 row_shr:1 row_mask:0xf bank_mask:0xf
	v_fmac_f32_dpp v217, v69, v149 row_shr:1 row_mask:0xf bank_mask:0xf
	v_fmac_f32_dpp v194, v76, v128 row_shr:1 row_mask:0xf bank_mask:0xf
	v_fmac_f32_dpp v218, v68, v144 row_shr:1 row_mask:0xf bank_mask:0xf
	v_fmac_f32_dpp v192, v92, v128 row_shr:1 row_mask:0xf bank_mask:0xf
	v_fmac_f32_dpp v216, v84, v144 row_shr:1 row_mask:0xf bank_mask:0xf
	v_fmac_f32_dpp v195, v77, v129 row_shr:1 row_mask:0xf bank_mask:0xf
	v_fmac_f32_dpp v219, v69, v145 row_shr:1 row_mask:0xf bank_mask:0xf
	v_fmac_f32_dpp v193, v93, v129 row_shr:1 row_mask:0xf bank_mask:0xf
	v_fmac_f32_dpp v217, v85, v145 row_shr:1 row_mask:0xf bank_mask:0xf
	v_pk_fma_f32 v[76:77], v[76:77], v[136:137], v[140:141]
	v_pk_fma_f32 v[68:69], v[68:69], v[152:153], v[156:157]
	v_pk_fma_f32 v[76:77], v[92:93], v[132:133], v[76:77]
	v_pk_fma_f32 v[68:69], v[84:85], v[148:149], v[68:69]
	v_pk_fma_f32 v[76:77], v[108:109], v[128:129], v[76:77]
	v_pk_fma_f32 v[68:69], v[100:101], v[144:145], v[68:69]
	v_pk_fma_f32 v[92:93], v[92:93], v[136:137], v[140:141]
	v_pk_fma_f32 v[84:85], v[84:85], v[152:153], v[156:157]
	v_pk_fma_f32 v[92:93], v[108:109], v[132:133], v[92:93]
	v_pk_fma_f32 v[84:85], v[100:101], v[148:149], v[84:85]
	v_pk_fma_f32 v[92:93], v[124:125], v[128:129], v[92:93]
	v_pk_fma_f32 v[84:85], v[116:117], v[144:145], v[84:85]
	v_pk_mul_f32 v[220:221], v[192:193], s[34:35]
	v_pk_mul_f32 v[222:223], v[194:195], s[34:35]
	v_exp_f32_e32 v220, v220
	v_exp_f32_e32 v222, v222
	v_exp_f32_e32 v221, v221
	v_exp_f32_e32 v223, v223
	v_pk_add_f32 v[220:221], v[220:221], s[36:37]
	v_pk_add_f32 v[222:223], v[222:223], s[36:37]
	v_rcp_f32_e32 v220, v220
	v_rcp_f32_e32 v222, v222
	v_rcp_f32_e32 v221, v221
	v_rcp_f32_e32 v223, v223
	v_pk_mul_f32 v[192:193], v[192:193], v[216:217]
	v_pk_mul_f32 v[194:195], v[194:195], v[218:219]
	v_pk_mul_f32 v[124:125], v[192:193], v[220:221]
	v_pk_mul_f32 v[108:109], v[194:195], v[222:223]
	v_pk_mul_f32 v[220:221], v[76:77], s[34:35]
	v_pk_mul_f32 v[222:223], v[92:93], s[34:35]
	v_exp_f32_e32 v220, v220
	v_exp_f32_e32 v222, v222
	v_exp_f32_e32 v221, v221
	v_exp_f32_e32 v223, v223
	v_pk_add_f32 v[220:221], v[220:221], s[36:37]
	v_pk_add_f32 v[222:223], v[222:223], s[36:37]
	v_rcp_f32_e32 v220, v220
	v_rcp_f32_e32 v222, v222
	v_rcp_f32_e32 v221, v221
	v_rcp_f32_e32 v223, v223
	v_pk_mul_f32 v[76:77], v[76:77], v[68:69]
	v_pk_mul_f32 v[92:93], v[92:93], v[84:85]
	v_pk_mul_f32 v[76:77], v[76:77], v[220:221]
	v_pk_mul_f32 v[92:93], v[92:93], v[222:223]
	v_pk_fma_f32 v[192:193], v[126:127], v[138:139], v[142:143]
	v_pk_fma_f32 v[216:217], v[118:119], v[154:155], v[158:159]
	v_pk_fma_f32 v[194:195], v[110:111], v[138:139], v[142:143]
	v_pk_fma_f32 v[218:219], v[102:103], v[154:155], v[158:159]
	v_fmac_f32_dpp v192, v78, v134 row_shr:1 row_mask:0xf bank_mask:0xf
	v_fmac_f32_dpp v216, v70, v150 row_shr:1 row_mask:0xf bank_mask:0xf
	v_pk_fma_f32 v[194:195], v[126:127], v[134:135], v[194:195]
	v_pk_fma_f32 v[218:219], v[118:119], v[150:151], v[218:219]
	v_fmac_f32_dpp v193, v79, v135 row_shr:1 row_mask:0xf bank_mask:0xf
	v_fmac_f32_dpp v217, v71, v151 row_shr:1 row_mask:0xf bank_mask:0xf
	v_fmac_f32_dpp v194, v78, v130 row_shr:1 row_mask:0xf bank_mask:0xf
	v_fmac_f32_dpp v218, v70, v146 row_shr:1 row_mask:0xf bank_mask:0xf
	v_fmac_f32_dpp v192, v94, v130 row_shr:1 row_mask:0xf bank_mask:0xf
	v_fmac_f32_dpp v216, v86, v146 row_shr:1 row_mask:0xf bank_mask:0xf
	v_fmac_f32_dpp v195, v79, v131 row_shr:1 row_mask:0xf bank_mask:0xf
	v_fmac_f32_dpp v219, v71, v147 row_shr:1 row_mask:0xf bank_mask:0xf
	v_fmac_f32_dpp v193, v95, v131 row_shr:1 row_mask:0xf bank_mask:0xf
	v_fmac_f32_dpp v217, v87, v147 row_shr:1 row_mask:0xf bank_mask:0xf
	v_pk_fma_f32 v[78:79], v[78:79], v[138:139], v[142:143]
	v_pk_fma_f32 v[70:71], v[70:71], v[154:155], v[158:159]
	v_pk_fma_f32 v[78:79], v[94:95], v[134:135], v[78:79]
	v_pk_fma_f32 v[70:71], v[86:87], v[150:151], v[70:71]
	v_pk_fma_f32 v[78:79], v[110:111], v[130:131], v[78:79]
	v_pk_fma_f32 v[70:71], v[102:103], v[146:147], v[70:71]
	v_pk_fma_f32 v[94:95], v[94:95], v[138:139], v[142:143]
	v_pk_fma_f32 v[86:87], v[86:87], v[154:155], v[158:159]
	v_pk_fma_f32 v[94:95], v[110:111], v[134:135], v[94:95]
	v_pk_fma_f32 v[86:87], v[102:103], v[150:151], v[86:87]
	v_pk_fma_f32 v[94:95], v[126:127], v[130:131], v[94:95]
	v_pk_fma_f32 v[86:87], v[118:119], v[146:147], v[86:87]
	v_pk_mul_f32 v[220:221], v[192:193], s[34:35]
	v_pk_mul_f32 v[222:223], v[194:195], s[34:35]
	v_exp_f32_e32 v220, v220
	v_exp_f32_e32 v222, v222
	v_exp_f32_e32 v221, v221
	v_exp_f32_e32 v223, v223
	v_pk_add_f32 v[220:221], v[220:221], s[36:37]
	v_pk_add_f32 v[222:223], v[222:223], s[36:37]
	v_rcp_f32_e32 v220, v220
	v_rcp_f32_e32 v222, v222
	v_rcp_f32_e32 v221, v221
	v_rcp_f32_e32 v223, v223
	v_pk_mul_f32 v[192:193], v[192:193], v[216:217]
	v_pk_mul_f32 v[194:195], v[194:195], v[218:219]
	v_pk_mul_f32 v[126:127], v[192:193], v[220:221]
	v_pk_mul_f32 v[110:111], v[194:195], v[222:223]
	v_pk_mul_f32 v[220:221], v[78:79], s[34:35]
	v_pk_mul_f32 v[222:223], v[94:95], s[34:35]
	v_exp_f32_e32 v220, v220
	v_exp_f32_e32 v222, v222
; __device__ __forceinline__ float sigmoidf_(float x) { return __builtin_amdgcn_rcpf(1.0f + __expf(-x)); }
; __device__ __forceinline__ void conv_phase(const Params& p, int layer) {
;     ...
;                 for (int e = 0; e < 8; ++e) {
;                     const float G = wg[0][e] * g2[e] + wg[1][e] * g1[e] + wg[2][e] * g0[e] + bg[e];
;                     const float V = wv[0][e] * v2[e] + wv[1][e] * v1[e] + wv[2][e] * v0[e] + bv[e];
;                     o[e] = G * sigmoidf_(G) * V;
;                     g2[e] = g1[e]; g1[e] = g0[e]; v2[e] = v1[e]; v1[e] = v0[e];
;                 }
	v_exp_f32_e32 v221, v221
	v_exp_f32_e32 v223, v223
	v_pk_add_f32 v[220:221], v[220:221], s[36:37]
	v_pk_add_f32 v[222:223], v[222:223], s[36:37]
	v_rcp_f32_e32 v220, v220
	v_rcp_f32_e32 v222, v222
	v_rcp_f32_e32 v221, v221
	v_rcp_f32_e32 v223, v223
	v_pk_mul_f32 v[78:79], v[78:79], v[70:71]
	v_pk_mul_f32 v[94:95], v[94:95], v[86:87]
	v_pk_mul_f32 v[78:79], v[78:79], v[220:221]
	v_pk_mul_f32 v[94:95], v[94:95], v[222:223]
	v_pk_fma_f32 v[192:193], v[60:61], v[136:137], v[140:141]
	v_pk_fma_f32 v[216:217], v[52:53], v[152:153], v[156:157]
	v_pk_fma_f32 v[194:195], v[44:45], v[136:137], v[140:141]
	v_pk_fma_f32 v[218:219], v[36:37], v[152:153], v[156:157]
	v_fmac_f32_dpp v192, v12, v132 row_shr:1 row_mask:0xf bank_mask:0xf
	v_fmac_f32_dpp v216, v4, v148 row_shr:1 row_mask:0xf bank_mask:0xf
	v_pk_fma_f32 v[194:195], v[60:61], v[132:133], v[194:195]
	v_pk_fma_f32 v[218:219], v[52:53], v[148:149], v[218:219]
	v_fmac_f32_dpp v193, v13, v133 row_shr:1 row_mask:0xf bank_mask:0xf
	v_fmac_f32_dpp v217, v5, v149 row_shr:1 row_mask:0xf bank_mask:0xf
	v_fmac_f32_dpp v194, v12, v128 row_shr:1 row_mask:0xf bank_mask:0xf
	v_fmac_f32_dpp v218, v4, v144 row_shr:1 row_mask:0xf bank_mask:0xf
	v_fmac_f32_dpp v192, v28, v128 row_shr:1 row_mask:0xf bank_mask:0xf
	v_fmac_f32_dpp v216, v20, v144 row_shr:1 row_mask:0xf bank_mask:0xf
	v_fmac_f32_dpp v195, v13, v129 row_shr:1 row_mask:0xf bank_mask:0xf
	v_fmac_f32_dpp v219, v5, v145 row_shr:1 row_mask:0xf bank_mask:0xf
	v_fmac_f32_dpp v193, v29, v129 row_shr:1 row_mask:0xf bank_mask:0xf
	v_fmac_f32_dpp v217, v21, v145 row_shr:1 row_mask:0xf bank_mask:0xf
	v_pk_fma_f32 v[12:13], v[12:13], v[136:137], v[140:141]
	v_pk_fma_f32 v[4:5], v[4:5], v[152:153], v[156:157]
	v_pk_fma_f32 v[12:13], v[28:29], v[132:133], v[12:13]
	v_pk_fma_f32 v[4:5], v[20:21], v[148:149], v[4:5]
	v_pk_fma_f32 v[12:13], v[44:45], v[128:129], v[12:13]
	v_pk_fma_f32 v[4:5], v[36:37], v[144:145], v[4:5]
	v_pk_fma_f32 v[28:29], v[28:29], v[136:137], v[140:141]
	v_pk_fma_f32 v[20:21], v[20:21], v[152:153], v[156:157]
	v_pk_fma_f32 v[28:29], v[44:45], v[132:133], v[28:29]
	v_pk_fma_f32 v[20:21], v[36:37], v[148:149], v[20:21]
	v_pk_fma_f32 v[28:29], v[60:61], v[128:129], v[28:29]
	v_pk_fma_f32 v[20:21], v[52:53], v[144:145], v[20:21]
	v_pk_mul_f32 v[220:221], v[192:193], s[34:35]
	v_pk_mul_f32 v[222:223], v[194:195], s[34:35]
	v_exp_f32_e32 v220, v220
	v_exp_f32_e32 v222, v222
	v_exp_f32_e32 v221, v221
	v_exp_f32_e32 v223, v223
	v_pk_add_f32 v[220:221], v[220:221], s[36:37]
	v_pk_add_f32 v[222:223], v[222:223], s[36:37]
	v_rcp_f32_e32 v220, v220
	v_rcp_f32_e32 v222, v222
	v_rcp_f32_e32 v221, v221
	v_rcp_f32_e32 v223, v223
	v_pk_mul_f32 v[192:193], v[192:193], v[216:217]
	v_pk_mul_f32 v[194:195], v[194:195], v[218:219]
	v_pk_mul_f32 v[60:61], v[192:193], v[220:221]
	v_pk_mul_f32 v[44:45], v[194:195], v[222:223]
	v_pk_mul_f32 v[220:221], v[12:13], s[34:35]
	v_pk_mul_f32 v[222:223], v[28:29], s[34:35]
	v_exp_f32_e32 v220, v220
	v_exp_f32_e32 v222, v222
	v_exp_f32_e32 v221, v221
	v_exp_f32_e32 v223, v223
	v_pk_add_f32 v[220:221], v[220:221], s[36:37]
	v_pk_add_f32 v[222:223], v[222:223], s[36:37]
	v_rcp_f32_e32 v220, v220
	v_rcp_f32_e32 v222, v222
	v_rcp_f32_e32 v221, v221
	v_rcp_f32_e32 v223, v223
	v_pk_mul_f32 v[12:13], v[12:13], v[4:5]
	v_pk_mul_f32 v[28:29], v[28:29], v[20:21]
	v_pk_mul_f32 v[12:13], v[12:13], v[220:221]
	v_pk_mul_f32 v[28:29], v[28:29], v[222:223]
	v_pk_fma_f32 v[192:193], v[62:63], v[138:139], v[142:143]
	v_pk_fma_f32 v[216:217], v[54:55], v[154:155], v[158:159]
	v_pk_fma_f32 v[194:195], v[46:47], v[138:139], v[142:143]
	v_pk_fma_f32 v[218:219], v[38:39], v[154:155], v[158:159]
	v_fmac_f32_dpp v192, v14, v134 row_shr:1 row_mask:0xf bank_mask:0xf
	v_fmac_f32_dpp v216, v6, v150 row_shr:1 row_mask:0xf bank_mask:0xf
	v_pk_fma_f32 v[194:195], v[62:63], v[134:135], v[194:195]
	v_pk_fma_f32 v[218:219], v[54:55], v[150:151], v[218:219]
	v_fmac_f32_dpp v193, v15, v135 row_shr:1 row_mask:0xf bank_mask:0xf
	v_fmac_f32_dpp v217, v7, v151 row_shr:1 row_mask:0xf bank_mask:0xf
	v_fmac_f32_dpp v194, v14, v130 row_shr:1 row_mask:0xf bank_mask:0xf
	v_fmac_f32_dpp v218, v6, v146 row_shr:1 row_mask:0xf bank_mask:0xf
	v_fmac_f32_dpp v192, v30, v130 row_shr:1 row_mask:0xf bank_mask:0xf
	v_fmac_f32_dpp v216, v22, v146 row_shr:1 row_mask:0xf bank_mask:0xf
	v_fmac_f32_dpp v195, v15, v131 row_shr:1 row_mask:0xf bank_mask:0xf
	v_fmac_f32_dpp v219, v7, v147 row_shr:1 row_mask:0xf bank_mask:0xf
	v_fmac_f32_dpp v193, v31, v131 row_shr:1 row_mask:0xf bank_mask:0xf
	v_fmac_f32_dpp v217, v23, v147 row_shr:1 row_mask:0xf bank_mask:0xf
	v_pk_fma_f32 v[14:15], v[14:15], v[138:139], v[142:143]
	v_pk_fma_f32 v[6:7], v[6:7], v[154:155], v[158:159]
	v_pk_fma_f32 v[14:15], v[30:31], v[134:135], v[14:15]
	v_pk_fma_f32 v[6:7], v[22:23], v[150:151], v[6:7]
	v_pk_fma_f32 v[14:15], v[46:47], v[130:131], v[14:15]
	v_pk_fma_f32 v[6:7], v[38:39], v[146:147], v[6:7]
	v_pk_fma_f32 v[30:31], v[30:31], v[138:139], v[142:143]
	v_pk_fma_f32 v[22:23], v[22:23], v[154:155], v[158:159]
	v_pk_fma_f32 v[30:31], v[46:47], v[134:135], v[30:31]
	v_pk_fma_f32 v[22:23], v[38:39], v[150:151], v[22:23]
	v_pk_fma_f32 v[30:31], v[62:63], v[130:131], v[30:31]
	v_pk_fma_f32 v[22:23], v[54:55], v[146:147], v[22:23]
	v_pk_mul_f32 v[220:221], v[192:193], s[34:35]
	v_pk_mul_f32 v[222:223], v[194:195], s[34:35]
	v_exp_f32_e32 v220, v220
	v_exp_f32_e32 v222, v222
	v_exp_f32_e32 v221, v221
	v_exp_f32_e32 v223, v223
	v_pk_add_f32 v[220:221], v[220:221], s[36:37]
	v_pk_add_f32 v[222:223], v[222:223], s[36:37]
	v_rcp_f32_e32 v220, v220
	v_rcp_f32_e32 v222, v222
	v_rcp_f32_e32 v221, v221
	v_rcp_f32_e32 v223, v223
	v_pk_mul_f32 v[192:193], v[192:193], v[216:217]
	v_pk_mul_f32 v[194:195], v[194:195], v[218:219]
	v_pk_mul_f32 v[62:63], v[192:193], v[220:221]
	v_pk_mul_f32 v[46:47], v[194:195], v[222:223]
	v_pk_mul_f32 v[220:221], v[14:15], s[34:35]
	v_pk_mul_f32 v[222:223], v[30:31], s[34:35]
	v_exp_f32_e32 v220, v220
	v_exp_f32_e32 v222, v222
	v_exp_f32_e32 v221, v221
	v_exp_f32_e32 v223, v223
	v_pk_add_f32 v[220:221], v[220:221], s[36:37]
	v_pk_add_f32 v[222:223], v[222:223], s[36:37]
	v_rcp_f32_e32 v220, v220
	v_rcp_f32_e32 v222, v222
	v_rcp_f32_e32 v221, v221
	v_rcp_f32_e32 v223, v223
	v_pk_mul_f32 v[14:15], v[14:15], v[6:7]
	v_pk_mul_f32 v[30:31], v[30:31], v[22:23]
	v_pk_mul_f32 v[14:15], v[14:15], v[220:221]
	v_pk_mul_f32 v[30:31], v[30:31], v[222:223]
	s_waitcnt vmcnt(0)
; __device__ __forceinline__ float sigmoidf_(float x) { return __builtin_amdgcn_rcpf(1.0f + __expf(-x)); }
; __device__ __forceinline__ void conv_phase(const Params& p, int layer) {
;     ...
;                 for (int e = 0; e < 8; ++e) {
;                     const float G = wg[0][e] * g2[e] + wg[1][e] * g1[e] + wg[2][e] * g0[e] + bg[e];
;                     const float V = wv[0][e] * v2[e] + wv[1][e] * v1[e] + wv[2][e] * v0[e] + bv[e];
;                     o[e] = G * sigmoidf_(G) * V;
;                     g2[e] = g1[e]; g1[e] = g0[e]; v2[e] = v1[e]; v1[e] = v0[e];
;                 }
	v_pk_fma_f32 v[192:193], v[120:121], v[168:169], v[172:173]
	v_pk_fma_f32 v[216:217], v[112:113], v[184:185], v[188:189]
	v_pk_fma_f32 v[194:195], v[104:105], v[168:169], v[172:173]
	v_pk_fma_f32 v[218:219], v[96:97], v[184:185], v[188:189]
	v_fmac_f32_dpp v192, v72, v164 row_shr:1 row_mask:0xf bank_mask:0xf
	v_fmac_f32_dpp v216, v64, v180 row_shr:1 row_mask:0xf bank_mask:0xf
	v_pk_fma_f32 v[194:195], v[120:121], v[164:165], v[194:195]
	v_pk_fma_f32 v[218:219], v[112:113], v[180:181], v[218:219]
	v_fmac_f32_dpp v193, v73, v165 row_shr:1 row_mask:0xf bank_mask:0xf
	v_fmac_f32_dpp v217, v65, v181 row_shr:1 row_mask:0xf bank_mask:0xf
	v_fmac_f32_dpp v194, v72, v160 row_shr:1 row_mask:0xf bank_mask:0xf
	v_fmac_f32_dpp v218, v64, v176 row_shr:1 row_mask:0xf bank_mask:0xf
	v_fmac_f32_dpp v192, v88, v160 row_shr:1 row_mask:0xf bank_mask:0xf
	v_fmac_f32_dpp v216, v80, v176 row_shr:1 row_mask:0xf bank_mask:0xf
	v_fmac_f32_dpp v195, v73, v161 row_shr:1 row_mask:0xf bank_mask:0xf
	v_fmac_f32_dpp v219, v65, v177 row_shr:1 row_mask:0xf bank_mask:0xf
	v_fmac_f32_dpp v193, v89, v161 row_shr:1 row_mask:0xf bank_mask:0xf
	v_fmac_f32_dpp v217, v81, v177 row_shr:1 row_mask:0xf bank_mask:0xf
	v_pk_fma_f32 v[72:73], v[72:73], v[168:169], v[172:173]
	v_pk_fma_f32 v[64:65], v[64:65], v[184:185], v[188:189]
	v_pk_fma_f32 v[72:73], v[88:89], v[164:165], v[72:73]
	v_pk_fma_f32 v[64:65], v[80:81], v[180:181], v[64:65]
	v_pk_fma_f32 v[72:73], v[104:105], v[160:161], v[72:73]
	v_pk_fma_f32 v[64:65], v[96:97], v[176:177], v[64:65]
	v_pk_fma_f32 v[88:89], v[88:89], v[168:169], v[172:173]
	v_pk_fma_f32 v[80:81], v[80:81], v[184:185], v[188:189]
	v_pk_fma_f32 v[88:89], v[104:105], v[164:165], v[88:89]
	v_pk_fma_f32 v[80:81], v[96:97], v[180:181], v[80:81]
	v_pk_fma_f32 v[88:89], v[120:121], v[160:161], v[88:89]
	v_pk_fma_f32 v[80:81], v[112:113], v[176:177], v[80:81]
	v_pk_mul_f32 v[220:221], v[192:193], s[34:35]
	v_pk_mul_f32 v[222:223], v[194:195], s[34:35]
	v_exp_f32_e32 v220, v220
	v_exp_f32_e32 v222, v222
	v_exp_f32_e32 v221, v221
	v_exp_f32_e32 v223, v223
	v_pk_add_f32 v[220:221], v[220:221], s[36:37]
	v_pk_add_f32 v[222:223], v[222:223], s[36:37]
	v_rcp_f32_e32 v220, v220
	v_rcp_f32_e32 v222, v222
	v_rcp_f32_e32 v221, v221
	v_rcp_f32_e32 v223, v223
	v_pk_mul_f32 v[192:193], v[192:193], v[216:217]
	v_pk_mul_f32 v[194:195], v[194:195], v[218:219]
	v_pk_mul_f32 v[120:121], v[192:193], v[220:221]
	v_pk_mul_f32 v[104:105], v[194:195], v[222:223]
	v_pk_mul_f32 v[220:221], v[72:73], s[34:35]
	v_pk_mul_f32 v[222:223], v[88:89], s[34:35]
	v_exp_f32_e32 v220, v220
	v_exp_f32_e32 v222, v222
	v_exp_f32_e32 v221, v221
	v_exp_f32_e32 v223, v223
	v_pk_add_f32 v[220:221], v[220:221], s[36:37]
	v_pk_add_f32 v[222:223], v[222:223], s[36:37]
	v_rcp_f32_e32 v220, v220
	v_rcp_f32_e32 v222, v222
	v_rcp_f32_e32 v221, v221
	v_rcp_f32_e32 v223, v223
	v_pk_mul_f32 v[72:73], v[72:73], v[64:65]
	v_pk_mul_f32 v[88:89], v[88:89], v[80:81]
	v_pk_mul_f32 v[72:73], v[72:73], v[220:221]
	v_pk_mul_f32 v[88:89], v[88:89], v[222:223]
	v_pk_fma_f32 v[192:193], v[122:123], v[170:171], v[174:175]
	v_pk_fma_f32 v[216:217], v[114:115], v[186:187], v[190:191]
	v_pk_fma_f32 v[194:195], v[106:107], v[170:171], v[174:175]
	v_pk_fma_f32 v[218:219], v[98:99], v[186:187], v[190:191]
	v_fmac_f32_dpp v192, v74, v166 row_shr:1 row_mask:0xf bank_mask:0xf
	v_fmac_f32_dpp v216, v66, v182 row_shr:1 row_mask:0xf bank_mask:0xf
	v_pk_fma_f32 v[194:195], v[122:123], v[166:167], v[194:195]
	v_pk_fma_f32 v[218:219], v[114:115], v[182:183], v[218:219]
	v_fmac_f32_dpp v193, v75, v167 row_shr:1 row_mask:0xf bank_mask:0xf
	v_fmac_f32_dpp v217, v67, v183 row_shr:1 row_mask:0xf bank_mask:0xf
	v_fmac_f32_dpp v194, v74, v162 row_shr:1 row_mask:0xf bank_mask:0xf
	v_fmac_f32_dpp v218, v66, v178 row_shr:1 row_mask:0xf bank_mask:0xf
	v_fmac_f32_dpp v192, v90, v162 row_shr:1 row_mask:0xf bank_mask:0xf
	v_fmac_f32_dpp v216, v82, v178 row_shr:1 row_mask:0xf bank_mask:0xf
	v_fmac_f32_dpp v195, v75, v163 row_shr:1 row_mask:0xf bank_mask:0xf
	v_fmac_f32_dpp v219, v67, v179 row_shr:1 row_mask:0xf bank_mask:0xf
	v_fmac_f32_dpp v193, v91, v163 row_shr:1 row_mask:0xf bank_mask:0xf
	v_fmac_f32_dpp v217, v83, v179 row_shr:1 row_mask:0xf bank_mask:0xf
	v_pk_fma_f32 v[74:75], v[74:75], v[170:171], v[174:175]
	v_pk_fma_f32 v[66:67], v[66:67], v[186:187], v[190:191]
	v_pk_fma_f32 v[74:75], v[90:91], v[166:167], v[74:75]
	v_pk_fma_f32 v[66:67], v[82:83], v[182:183], v[66:67]
	v_pk_fma_f32 v[74:75], v[106:107], v[162:163], v[74:75]
	v_pk_fma_f32 v[66:67], v[98:99], v[178:179], v[66:67]
	v_pk_fma_f32 v[90:91], v[90:91], v[170:171], v[174:175]
	v_pk_fma_f32 v[82:83], v[82:83], v[186:187], v[190:191]
	v_pk_fma_f32 v[90:91], v[106:107], v[166:167], v[90:91]
	v_pk_fma_f32 v[82:83], v[98:99], v[182:183], v[82:83]
	v_pk_fma_f32 v[90:91], v[122:123], v[162:163], v[90:91]
	v_pk_fma_f32 v[82:83], v[114:115], v[178:179], v[82:83]
	v_pk_mul_f32 v[220:221], v[192:193], s[34:35]
	v_pk_mul_f32 v[222:223], v[194:195], s[34:35]
	v_exp_f32_e32 v220, v220
	v_exp_f32_e32 v222, v222
	v_exp_f32_e32 v221, v221
	v_exp_f32_e32 v223, v223
	v_pk_add_f32 v[220:221], v[220:221], s[36:37]
	v_pk_add_f32 v[222:223], v[222:223], s[36:37]
	v_rcp_f32_e32 v220, v220
	v_rcp_f32_e32 v222, v222
	v_rcp_f32_e32 v221, v221
	v_rcp_f32_e32 v223, v223
	v_pk_mul_f32 v[192:193], v[192:193], v[216:217]
	v_pk_mul_f32 v[194:195], v[194:195], v[218:219]
	v_pk_mul_f32 v[122:123], v[192:193], v[220:221]
	v_pk_mul_f32 v[106:107], v[194:195], v[222:223]
	v_pk_mul_f32 v[220:221], v[74:75], s[34:35]
	v_pk_mul_f32 v[222:223], v[90:91], s[34:35]
	v_exp_f32_e32 v220, v220
	v_exp_f32_e32 v222, v222
; __device__ __forceinline__ float sigmoidf_(float x) { return __builtin_amdgcn_rcpf(1.0f + __expf(-x)); }
; __device__ __forceinline__ void conv_phase(const Params& p, int layer) {
;     ...
;                 for (int e = 0; e < 8; ++e) {
;                     const float G = wg[0][e] * g2[e] + wg[1][e] * g1[e] + wg[2][e] * g0[e] + bg[e];
;                     const float V = wv[0][e] * v2[e] + wv[1][e] * v1[e] + wv[2][e] * v0[e] + bv[e];
;                     o[e] = G * sigmoidf_(G) * V;
;                     g2[e] = g1[e]; g1[e] = g0[e]; v2[e] = v1[e]; v1[e] = v0[e];
;                 }
	v_exp_f32_e32 v221, v221
	v_exp_f32_e32 v223, v223
	v_pk_add_f32 v[220:221], v[220:221], s[36:37]
	v_pk_add_f32 v[222:223], v[222:223], s[36:37]
	v_rcp_f32_e32 v220, v220
	v_rcp_f32_e32 v222, v222
	v_rcp_f32_e32 v221, v221
	v_rcp_f32_e32 v223, v223
	v_pk_mul_f32 v[74:75], v[74:75], v[66:67]
	v_pk_mul_f32 v[90:91], v[90:91], v[82:83]
	v_pk_mul_f32 v[74:75], v[74:75], v[220:221]
	v_pk_mul_f32 v[90:91], v[90:91], v[222:223]
	v_pk_fma_f32 v[192:193], v[56:57], v[168:169], v[172:173]
	v_pk_fma_f32 v[216:217], v[48:49], v[184:185], v[188:189]
	v_pk_fma_f32 v[194:195], v[40:41], v[168:169], v[172:173]
	v_pk_fma_f32 v[218:219], v[32:33], v[184:185], v[188:189]
	v_fmac_f32_dpp v192, v8, v164 row_shr:1 row_mask:0xf bank_mask:0xf
	v_fmac_f32_dpp v216, v0, v180 row_shr:1 row_mask:0xf bank_mask:0xf
	v_pk_fma_f32 v[194:195], v[56:57], v[164:165], v[194:195]
	v_pk_fma_f32 v[218:219], v[48:49], v[180:181], v[218:219]
	v_fmac_f32_dpp v193, v9, v165 row_shr:1 row_mask:0xf bank_mask:0xf
	v_fmac_f32_dpp v217, v1, v181 row_shr:1 row_mask:0xf bank_mask:0xf
	v_fmac_f32_dpp v194, v8, v160 row_shr:1 row_mask:0xf bank_mask:0xf
	v_fmac_f32_dpp v218, v0, v176 row_shr:1 row_mask:0xf bank_mask:0xf
	v_fmac_f32_dpp v192, v24, v160 row_shr:1 row_mask:0xf bank_mask:0xf
	v_fmac_f32_dpp v216, v16, v176 row_shr:1 row_mask:0xf bank_mask:0xf
	v_fmac_f32_dpp v195, v9, v161 row_shr:1 row_mask:0xf bank_mask:0xf
	v_fmac_f32_dpp v219, v1, v177 row_shr:1 row_mask:0xf bank_mask:0xf
	v_fmac_f32_dpp v193, v25, v161 row_shr:1 row_mask:0xf bank_mask:0xf
	v_fmac_f32_dpp v217, v17, v177 row_shr:1 row_mask:0xf bank_mask:0xf
	v_pk_fma_f32 v[8:9], v[8:9], v[168:169], v[172:173]
	v_pk_fma_f32 v[0:1], v[0:1], v[184:185], v[188:189]
	v_pk_fma_f32 v[8:9], v[24:25], v[164:165], v[8:9]
	v_pk_fma_f32 v[0:1], v[16:17], v[180:181], v[0:1]
	v_pk_fma_f32 v[8:9], v[40:41], v[160:161], v[8:9]
	v_pk_fma_f32 v[0:1], v[32:33], v[176:177], v[0:1]
	v_pk_fma_f32 v[24:25], v[24:25], v[168:169], v[172:173]
	v_pk_fma_f32 v[16:17], v[16:17], v[184:185], v[188:189]
	v_pk_fma_f32 v[24:25], v[40:41], v[164:165], v[24:25]
	v_pk_fma_f32 v[16:17], v[32:33], v[180:181], v[16:17]
	v_pk_fma_f32 v[24:25], v[56:57], v[160:161], v[24:25]
	v_pk_fma_f32 v[16:17], v[48:49], v[176:177], v[16:17]
	v_pk_mul_f32 v[220:221], v[192:193], s[34:35]
	v_pk_mul_f32 v[222:223], v[194:195], s[34:35]
	v_exp_f32_e32 v220, v220
	v_exp_f32_e32 v222, v222
	v_exp_f32_e32 v221, v221
	v_exp_f32_e32 v223, v223
	v_pk_add_f32 v[220:221], v[220:221], s[36:37]
	v_pk_add_f32 v[222:223], v[222:223], s[36:37]
	v_rcp_f32_e32 v220, v220
	v_rcp_f32_e32 v222, v222
	v_rcp_f32_e32 v221, v221
	v_rcp_f32_e32 v223, v223
	v_pk_mul_f32 v[192:193], v[192:193], v[216:217]
	v_pk_mul_f32 v[194:195], v[194:195], v[218:219]
	v_pk_mul_f32 v[56:57], v[192:193], v[220:221]
	v_pk_mul_f32 v[40:41], v[194:195], v[222:223]
	v_pk_mul_f32 v[220:221], v[8:9], s[34:35]
	v_pk_mul_f32 v[222:223], v[24:25], s[34:35]
	v_exp_f32_e32 v220, v220
	v_exp_f32_e32 v222, v222
	v_exp_f32_e32 v221, v221
	v_exp_f32_e32 v223, v223
	v_pk_add_f32 v[220:221], v[220:221], s[36:37]
	v_pk_add_f32 v[222:223], v[222:223], s[36:37]
	v_rcp_f32_e32 v220, v220
	v_rcp_f32_e32 v222, v222
	v_rcp_f32_e32 v221, v221
	v_rcp_f32_e32 v223, v223
	v_pk_mul_f32 v[8:9], v[8:9], v[0:1]
	v_pk_mul_f32 v[24:25], v[24:25], v[16:17]
	v_pk_mul_f32 v[8:9], v[8:9], v[220:221]
	v_pk_mul_f32 v[24:25], v[24:25], v[222:223]
	v_pk_fma_f32 v[192:193], v[58:59], v[170:171], v[174:175]
	v_pk_fma_f32 v[216:217], v[50:51], v[186:187], v[190:191]
	v_pk_fma_f32 v[194:195], v[42:43], v[170:171], v[174:175]
	v_pk_fma_f32 v[218:219], v[34:35], v[186:187], v[190:191]
	v_fmac_f32_dpp v192, v10, v166 row_shr:1 row_mask:0xf bank_mask:0xf
	v_fmac_f32_dpp v216, v2, v182 row_shr:1 row_mask:0xf bank_mask:0xf
	v_pk_fma_f32 v[194:195], v[58:59], v[166:167], v[194:195]
	v_pk_fma_f32 v[218:219], v[50:51], v[182:183], v[218:219]
	v_fmac_f32_dpp v193, v11, v167 row_shr:1 row_mask:0xf bank_mask:0xf
	v_fmac_f32_dpp v217, v3, v183 row_shr:1 row_mask:0xf bank_mask:0xf
	v_fmac_f32_dpp v194, v10, v162 row_shr:1 row_mask:0xf bank_mask:0xf
	v_fmac_f32_dpp v218, v2, v178 row_shr:1 row_mask:0xf bank_mask:0xf
	v_fmac_f32_dpp v192, v26, v162 row_shr:1 row_mask:0xf bank_mask:0xf
	v_fmac_f32_dpp v216, v18, v178 row_shr:1 row_mask:0xf bank_mask:0xf
; __device__ __forceinline__ u32x4 pack8(f32x4 a, f32x4 b) { u32x4 w; w.x = pk2(a[0], a[1]); w.y = pk2(a[2], a[3]); w.z = pk2(b[0], b[1]); w.w = pk2(b[2], b[3]); return w; }
; __device__ __forceinline__ float sigmoidf_(float x) { return __builtin_amdgcn_rcpf(1.0f + __expf(-x)); }
; __device__ __forceinline__ void conv_phase(const Params& p, int layer) {
;     ...
;                 for (int e = 0; e < 8; ++e) {
;                     const float G = wg[0][e] * g2[e] + wg[1][e] * g1[e] + wg[2][e] * g0[e] + bg[e];
;                     const float V = wv[0][e] * v2[e] + wv[1][e] * v1[e] + wv[2][e] * v0[e] + bv[e];
;                     o[e] = G * sigmoidf_(G) * V;
;                     g2[e] = g1[e]; g1[e] = g0[e]; v2[e] = v1[e]; v1[e] = v0[e];
;                 }
;                 *(u32x4*)(act + (size_t)(r0 + i0 + i) * DFF + f) = pack8((f32x4){o[0], o[1], o[2], o[3]}, (f32x4){o[4], o[5], o[6], o[7]});
	v_fmac_f32_dpp v195, v11, v163 row_shr:1 row_mask:0xf bank_mask:0xf
	v_fmac_f32_dpp v219, v3, v179 row_shr:1 row_mask:0xf bank_mask:0xf
	v_fmac_f32_dpp v193, v27, v163 row_shr:1 row_mask:0xf bank_mask:0xf
	v_fmac_f32_dpp v217, v19, v179 row_shr:1 row_mask:0xf bank_mask:0xf
	v_pk_fma_f32 v[10:11], v[10:11], v[170:171], v[174:175]
	v_pk_fma_f32 v[2:3], v[2:3], v[186:187], v[190:191]
	v_pk_fma_f32 v[10:11], v[26:27], v[166:167], v[10:11]
	v_pk_fma_f32 v[2:3], v[18:19], v[182:183], v[2:3]
	v_pk_fma_f32 v[10:11], v[42:43], v[162:163], v[10:11]
	v_pk_fma_f32 v[2:3], v[34:35], v[178:179], v[2:3]
	v_pk_fma_f32 v[26:27], v[26:27], v[170:171], v[174:175]
	v_pk_fma_f32 v[18:19], v[18:19], v[186:187], v[190:191]
	v_pk_fma_f32 v[26:27], v[42:43], v[166:167], v[26:27]
	v_pk_fma_f32 v[18:19], v[34:35], v[182:183], v[18:19]
	v_pk_fma_f32 v[26:27], v[58:59], v[162:163], v[26:27]
	v_pk_fma_f32 v[18:19], v[50:51], v[178:179], v[18:19]
	v_pk_mul_f32 v[220:221], v[192:193], s[34:35]
	v_pk_mul_f32 v[222:223], v[194:195], s[34:35]
	v_exp_f32_e32 v220, v220
	v_exp_f32_e32 v222, v222
	v_exp_f32_e32 v221, v221
	v_exp_f32_e32 v223, v223
	v_pk_add_f32 v[220:221], v[220:221], s[36:37]
	v_pk_add_f32 v[222:223], v[222:223], s[36:37]
	v_rcp_f32_e32 v220, v220
	v_rcp_f32_e32 v222, v222
	v_rcp_f32_e32 v221, v221
	v_rcp_f32_e32 v223, v223
	v_pk_mul_f32 v[192:193], v[192:193], v[216:217]
	v_pk_mul_f32 v[194:195], v[194:195], v[218:219]
	v_pk_mul_f32 v[58:59], v[192:193], v[220:221]
	v_pk_mul_f32 v[42:43], v[194:195], v[222:223]
	v_pk_mul_f32 v[220:221], v[10:11], s[34:35]
	v_pk_mul_f32 v[222:223], v[26:27], s[34:35]
	v_exp_f32_e32 v220, v220
	v_exp_f32_e32 v222, v222
	v_exp_f32_e32 v221, v221
	v_exp_f32_e32 v223, v223
	v_pk_add_f32 v[220:221], v[220:221], s[36:37]
	v_pk_add_f32 v[222:223], v[222:223], s[36:37]
	v_rcp_f32_e32 v220, v220
	v_rcp_f32_e32 v222, v222
	v_rcp_f32_e32 v221, v221
	v_rcp_f32_e32 v223, v223
	v_pk_mul_f32 v[10:11], v[10:11], v[2:3]
	v_pk_mul_f32 v[26:27], v[26:27], v[18:19]
	v_pk_mul_f32 v[10:11], v[10:11], v[220:221]
	v_pk_mul_f32 v[26:27], v[26:27], v[222:223]
	v_readlane_b32 s0, v250, 38
	v_readlane_b32 s1, v250, 39
	s_movk_i32 s33, 0x1600
	v_and_b32_e32 v192, 15, v240
	v_lshl_add_u32 v192, v192, 1, v192
	v_add_u32_e32 v192, v240, v192
	v_lshl_add_u32 v220, v202, 1, s27
	v_mov_b32_e32 v221, v197
	v_mad_u64_u32 v[216:217], s[38:39], v192, s33, v[220:221]
	s_movk_i32 s34, 0x1600
	s_mov_b32 s35, 0
	s_mov_b32 s36, 0xabe00
	s_mov_b32 s37, 0
	v_lshl_add_u64 v[216:217], s[0:1], 0, v[216:217]
	v_cvt_pk_f16_f32 v112, v124, v125
	v_cvt_pk_f16_f32 v113, v126, v127
	v_cvt_pk_f16_f32 v114, v120, v121
	v_cvt_pk_f16_f32 v115, v122, v123
	v_lshl_add_u64 v[218:219], v[216:217], 0, s[34:35]
	global_store_dwordx4 v[216:217], v[112:115], off
	v_cvt_pk_f16_f32 v96, v108, v109
	v_cvt_pk_f16_f32 v97, v110, v111
	v_cvt_pk_f16_f32 v98, v104, v105
	v_cvt_pk_f16_f32 v99, v106, v107
	v_lshl_add_u64 v[216:217], v[218:219], 0, s[34:35]
	global_store_dwordx4 v[218:219], v[96:99], off
	v_cvt_pk_f16_f32 v80, v92, v93
	v_cvt_pk_f16_f32 v81, v94, v95
	v_cvt_pk_f16_f32 v82, v88, v89
	v_cvt_pk_f16_f32 v83, v90, v91
	v_lshl_add_u64 v[218:219], v[216:217], 0, s[34:35]
	global_store_dwordx4 v[216:217], v[80:83], off
	v_cvt_pk_f16_f32 v64, v76, v77
	v_cvt_pk_f16_f32 v65, v78, v79
	v_cvt_pk_f16_f32 v66, v72, v73
	v_cvt_pk_f16_f32 v67, v74, v75
	v_lshl_add_u64 v[216:217], v[218:219], 0, s[36:37]
	global_store_dwordx4 v[218:219], v[64:67], off
	v_cvt_pk_f16_f32 v48, v60, v61
	v_cvt_pk_f16_f32 v49, v62, v63
	v_cvt_pk_f16_f32 v50, v56, v57
	v_cvt_pk_f16_f32 v51, v58, v59
	v_lshl_add_u64 v[218:219], v[216:217], 0, s[34:35]
	global_store_dwordx4 v[216:217], v[48:51], off
	v_cvt_pk_f16_f32 v32, v44, v45
	v_cvt_pk_f16_f32 v33, v46, v47
	v_cvt_pk_f16_f32 v34, v40, v41
	v_cvt_pk_f16_f32 v35, v42, v43
	v_lshl_add_u64 v[216:217], v[218:219], 0, s[34:35]
	global_store_dwordx4 v[218:219], v[32:35], off
	v_cvt_pk_f16_f32 v16, v28, v29
	v_cvt_pk_f16_f32 v17, v30, v31
	v_cvt_pk_f16_f32 v18, v24, v25
	v_cvt_pk_f16_f32 v19, v26, v27
	v_lshl_add_u64 v[218:219], v[216:217], 0, s[34:35]
	global_store_dwordx4 v[216:217], v[16:19], off
	v_cvt_pk_f16_f32 v0, v12, v13
	v_cvt_pk_f16_f32 v1, v14, v15
	v_cvt_pk_f16_f32 v2, v8, v9
	v_cvt_pk_f16_f32 v3, v10, v11
	global_store_dwordx4 v[218:219], v[0:3], off
